# plus batched W2 fragment loads in compression MLP second GEMM, 64-deep w_ada load batches
# speedup vs baseline: 1.0444x; 1.0009x over previous
; DI void ada_task(const Params& p, int task, char* smem) {
;     ...
;   const float* w = p.in[3] + ((size_t)l * 1024 + kq * 256) * 6144 + n0 + j;
;   float a0 = 0.f, a1 = 0.f;
; #pragma unroll 8
;   for (int k = 0; k < 256; ++k) { const float wv = w[(size_t)k * 6144]; a0 += sc[kq * 256 + k] * wv; a1 += sc[1024 + kq * 256 + k] * wv; }
.LBB0_55:
	v_lshl_add_u64 v[160:161], v[6:7], 0, s[0:1]
	global_load_dword v30, v[160:161], off
	v_add_co_u32_e32 v160, vcc, 0x6000, v160
	s_nop 1
	v_addc_co_u32_e32 v161, vcc, 0, v161, vcc
	global_load_dword v32, v[160:161], off
	v_add_co_u32_e32 v160, vcc, 0x6000, v160
	s_nop 1
	v_addc_co_u32_e32 v161, vcc, 0, v161, vcc
	global_load_dword v34, v[160:161], off
	v_add_co_u32_e32 v160, vcc, 0x6000, v160
	s_nop 1
	v_addc_co_u32_e32 v161, vcc, 0, v161, vcc
	global_load_dword v36, v[160:161], off
	v_add_co_u32_e32 v160, vcc, 0x6000, v160
	s_nop 1
	v_addc_co_u32_e32 v161, vcc, 0, v161, vcc
	global_load_dword v38, v[160:161], off
	v_add_co_u32_e32 v160, vcc, 0x6000, v160
	s_nop 1
	v_addc_co_u32_e32 v161, vcc, 0, v161, vcc
	global_load_dword v40, v[160:161], off
	v_add_co_u32_e32 v160, vcc, 0x6000, v160
	s_nop 1
	v_addc_co_u32_e32 v161, vcc, 0, v161, vcc
	global_load_dword v42, v[160:161], off
	v_add_co_u32_e32 v160, vcc, 0x6000, v160
	s_nop 1
	v_addc_co_u32_e32 v161, vcc, 0, v161, vcc
	global_load_dword v44, v[160:161], off
	v_add_co_u32_e32 v160, vcc, 0x6000, v160
	s_nop 1
	v_addc_co_u32_e32 v161, vcc, 0, v161, vcc
	global_load_dword v46, v[160:161], off
	v_add_co_u32_e32 v160, vcc, 0x6000, v160
	s_nop 1
	v_addc_co_u32_e32 v161, vcc, 0, v161, vcc
	global_load_dword v48, v[160:161], off
	v_add_co_u32_e32 v160, vcc, 0x6000, v160
	s_nop 1
	v_addc_co_u32_e32 v161, vcc, 0, v161, vcc
	global_load_dword v50, v[160:161], off
	v_add_co_u32_e32 v160, vcc, 0x6000, v160
	s_nop 1
	v_addc_co_u32_e32 v161, vcc, 0, v161, vcc
	global_load_dword v52, v[160:161], off
	v_add_co_u32_e32 v160, vcc, 0x6000, v160
	s_nop 1
	v_addc_co_u32_e32 v161, vcc, 0, v161, vcc
	global_load_dword v54, v[160:161], off
	v_add_co_u32_e32 v160, vcc, 0x6000, v160
	s_nop 1
	v_addc_co_u32_e32 v161, vcc, 0, v161, vcc
	global_load_dword v56, v[160:161], off
	v_add_co_u32_e32 v160, vcc, 0x6000, v160
	s_nop 1
	v_addc_co_u32_e32 v161, vcc, 0, v161, vcc
	global_load_dword v58, v[160:161], off
	v_add_co_u32_e32 v160, vcc, 0x6000, v160
	s_nop 1
	v_addc_co_u32_e32 v161, vcc, 0, v161, vcc
	global_load_dword v60, v[160:161], off
	v_add_co_u32_e32 v160, vcc, 0x6000, v160
	s_nop 1
	v_addc_co_u32_e32 v161, vcc, 0, v161, vcc
	global_load_dword v62, v[160:161], off
	v_add_co_u32_e32 v160, vcc, 0x6000, v160
	s_nop 1
	v_addc_co_u32_e32 v161, vcc, 0, v161, vcc
	global_load_dword v64, v[160:161], off
	v_add_co_u32_e32 v160, vcc, 0x6000, v160
	s_nop 1
	v_addc_co_u32_e32 v161, vcc, 0, v161, vcc
	global_load_dword v66, v[160:161], off
	v_add_co_u32_e32 v160, vcc, 0x6000, v160
	s_nop 1
	v_addc_co_u32_e32 v161, vcc, 0, v161, vcc
	global_load_dword v68, v[160:161], off
	v_add_co_u32_e32 v160, vcc, 0x6000, v160
	s_nop 1
	v_addc_co_u32_e32 v161, vcc, 0, v161, vcc
	global_load_dword v70, v[160:161], off
	v_add_co_u32_e32 v160, vcc, 0x6000, v160
	s_nop 1
	v_addc_co_u32_e32 v161, vcc, 0, v161, vcc
	global_load_dword v72, v[160:161], off
	v_add_co_u32_e32 v160, vcc, 0x6000, v160
	s_nop 1
	v_addc_co_u32_e32 v161, vcc, 0, v161, vcc
	global_load_dword v74, v[160:161], off
	v_add_co_u32_e32 v160, vcc, 0x6000, v160
	s_nop 1
	v_addc_co_u32_e32 v161, vcc, 0, v161, vcc
	global_load_dword v76, v[160:161], off
	v_add_co_u32_e32 v160, vcc, 0x6000, v160
	s_nop 1
	v_addc_co_u32_e32 v161, vcc, 0, v161, vcc
	global_load_dword v78, v[160:161], off
	v_add_co_u32_e32 v160, vcc, 0x6000, v160
	s_nop 1
	v_addc_co_u32_e32 v161, vcc, 0, v161, vcc
	global_load_dword v80, v[160:161], off
	v_add_co_u32_e32 v160, vcc, 0x6000, v160
	s_nop 1
	v_addc_co_u32_e32 v161, vcc, 0, v161, vcc
	global_load_dword v82, v[160:161], off
	v_add_co_u32_e32 v160, vcc, 0x6000, v160
	s_nop 1
	v_addc_co_u32_e32 v161, vcc, 0, v161, vcc
	global_load_dword v84, v[160:161], off
	v_add_co_u32_e32 v160, vcc, 0x6000, v160
	s_nop 1
	v_addc_co_u32_e32 v161, vcc, 0, v161, vcc
	global_load_dword v86, v[160:161], off
	v_add_co_u32_e32 v160, vcc, 0x6000, v160
	s_nop 1
	v_addc_co_u32_e32 v161, vcc, 0, v161, vcc
	global_load_dword v88, v[160:161], off
	v_add_co_u32_e32 v160, vcc, 0x6000, v160
	s_nop 1
	v_addc_co_u32_e32 v161, vcc, 0, v161, vcc
	global_load_dword v90, v[160:161], off
	v_add_co_u32_e32 v160, vcc, 0x6000, v160
	s_nop 1
	v_addc_co_u32_e32 v161, vcc, 0, v161, vcc
	global_load_dword v92, v[160:161], off
	v_add_co_u32_e32 v160, vcc, 0x6000, v160
	s_nop 1
	v_addc_co_u32_e32 v161, vcc, 0, v161, vcc
	global_load_dword v94, v[160:161], off
	v_add_co_u32_e32 v160, vcc, 0x6000, v160
	s_nop 1
	v_addc_co_u32_e32 v161, vcc, 0, v161, vcc
	global_load_dword v96, v[160:161], off
	v_add_co_u32_e32 v160, vcc, 0x6000, v160
	s_nop 1
	v_addc_co_u32_e32 v161, vcc, 0, v161, vcc
	global_load_dword v98, v[160:161], off
	v_add_co_u32_e32 v160, vcc, 0x6000, v160
	s_nop 1
	v_addc_co_u32_e32 v161, vcc, 0, v161, vcc
	global_load_dword v100, v[160:161], off
	v_add_co_u32_e32 v160, vcc, 0x6000, v160
	s_nop 1
	v_addc_co_u32_e32 v161, vcc, 0, v161, vcc
	global_load_dword v102, v[160:161], off
	v_add_co_u32_e32 v160, vcc, 0x6000, v160
	s_nop 1
	v_addc_co_u32_e32 v161, vcc, 0, v161, vcc
	global_load_dword v104, v[160:161], off
	v_add_co_u32_e32 v160, vcc, 0x6000, v160
	s_nop 1
	v_addc_co_u32_e32 v161, vcc, 0, v161, vcc
	global_load_dword v106, v[160:161], off
	v_add_co_u32_e32 v160, vcc, 0x6000, v160
	s_nop 1
	v_addc_co_u32_e32 v161, vcc, 0, v161, vcc
	global_load_dword v108, v[160:161], off
	v_add_co_u32_e32 v160, vcc, 0x6000, v160
	s_nop 1
	v_addc_co_u32_e32 v161, vcc, 0, v161, vcc
	global_load_dword v110, v[160:161], off
	v_add_co_u32_e32 v160, vcc, 0x6000, v160
	s_nop 1
	v_addc_co_u32_e32 v161, vcc, 0, v161, vcc
	global_load_dword v112, v[160:161], off
	v_add_co_u32_e32 v160, vcc, 0x6000, v160
; DI void ada_task(const Params& p, int task, char* smem) {
;     ...
;   const float* w = p.in[3] + ((size_t)l * 1024 + kq * 256) * 6144 + n0 + j;
;   float a0 = 0.f, a1 = 0.f;
; #pragma unroll 8
;   for (int k = 0; k < 256; ++k) { const float wv = w[(size_t)k * 6144]; a0 += sc[kq * 256 + k] * wv; a1 += sc[1024 + kq * 256 + k] * wv; }
	s_nop 1
	v_addc_co_u32_e32 v161, vcc, 0, v161, vcc
	global_load_dword v114, v[160:161], off
	v_add_co_u32_e32 v160, vcc, 0x6000, v160
	s_nop 1
	v_addc_co_u32_e32 v161, vcc, 0, v161, vcc
	global_load_dword v116, v[160:161], off
	v_add_co_u32_e32 v160, vcc, 0x6000, v160
	s_nop 1
	v_addc_co_u32_e32 v161, vcc, 0, v161, vcc
	global_load_dword v118, v[160:161], off
	v_add_co_u32_e32 v160, vcc, 0x6000, v160
	s_nop 1
	v_addc_co_u32_e32 v161, vcc, 0, v161, vcc
	global_load_dword v120, v[160:161], off
	v_add_co_u32_e32 v160, vcc, 0x6000, v160
	s_nop 1
	v_addc_co_u32_e32 v161, vcc, 0, v161, vcc
	global_load_dword v122, v[160:161], off
	v_add_co_u32_e32 v160, vcc, 0x6000, v160
	s_nop 1
	v_addc_co_u32_e32 v161, vcc, 0, v161, vcc
	global_load_dword v124, v[160:161], off
	v_add_co_u32_e32 v160, vcc, 0x6000, v160
	s_nop 1
	v_addc_co_u32_e32 v161, vcc, 0, v161, vcc
	global_load_dword v126, v[160:161], off
	v_add_co_u32_e32 v160, vcc, 0x6000, v160
	s_nop 1
	v_addc_co_u32_e32 v161, vcc, 0, v161, vcc
	global_load_dword v128, v[160:161], off
	v_add_co_u32_e32 v160, vcc, 0x6000, v160
	s_nop 1
	v_addc_co_u32_e32 v161, vcc, 0, v161, vcc
	global_load_dword v130, v[160:161], off
	v_add_co_u32_e32 v160, vcc, 0x6000, v160
	s_nop 1
	v_addc_co_u32_e32 v161, vcc, 0, v161, vcc
	global_load_dword v132, v[160:161], off
	v_add_co_u32_e32 v160, vcc, 0x6000, v160
	s_nop 1
	v_addc_co_u32_e32 v161, vcc, 0, v161, vcc
	global_load_dword v134, v[160:161], off
	v_add_co_u32_e32 v160, vcc, 0x6000, v160
	s_nop 1
	v_addc_co_u32_e32 v161, vcc, 0, v161, vcc
	global_load_dword v136, v[160:161], off
	v_add_co_u32_e32 v160, vcc, 0x6000, v160
	s_nop 1
	v_addc_co_u32_e32 v161, vcc, 0, v161, vcc
	global_load_dword v138, v[160:161], off
	v_add_co_u32_e32 v160, vcc, 0x6000, v160
	s_nop 1
	v_addc_co_u32_e32 v161, vcc, 0, v161, vcc
	global_load_dword v140, v[160:161], off
	v_add_co_u32_e32 v160, vcc, 0x6000, v160
	s_nop 1
	v_addc_co_u32_e32 v161, vcc, 0, v161, vcc
	global_load_dword v142, v[160:161], off
	v_add_co_u32_e32 v160, vcc, 0x6000, v160
	s_nop 1
	v_addc_co_u32_e32 v161, vcc, 0, v161, vcc
	global_load_dword v144, v[160:161], off
	v_add_co_u32_e32 v160, vcc, 0x6000, v160
	s_nop 1
	v_addc_co_u32_e32 v161, vcc, 0, v161, vcc
	global_load_dword v146, v[160:161], off
	v_add_co_u32_e32 v160, vcc, 0x6000, v160
	s_nop 1
	v_addc_co_u32_e32 v161, vcc, 0, v161, vcc
	global_load_dword v148, v[160:161], off
	v_add_co_u32_e32 v160, vcc, 0x6000, v160
	s_nop 1
	v_addc_co_u32_e32 v161, vcc, 0, v161, vcc
	global_load_dword v150, v[160:161], off
	v_add_co_u32_e32 v160, vcc, 0x6000, v160
	s_nop 1
	v_addc_co_u32_e32 v161, vcc, 0, v161, vcc
	global_load_dword v152, v[160:161], off
	v_add_co_u32_e32 v160, vcc, 0x6000, v160
	s_nop 1
	v_addc_co_u32_e32 v161, vcc, 0, v161, vcc
	global_load_dword v154, v[160:161], off
	v_add_co_u32_e32 v160, vcc, 0x6000, v160
	s_nop 1
	v_addc_co_u32_e32 v161, vcc, 0, v161, vcc
	global_load_dword v156, v[160:161], off
	ds_read_b128 v[12:15], v0
	ds_read_b128 v[16:19], v0 offset:16
	ds_read_b128 v[20:23], v0 offset:4096
	s_mov_b32 s25, 0x2a000
	s_add_u32 s0, s0, 0x30000
	s_waitcnt lgkmcnt(2)
	v_mov_b32_e32 v28, v12
	s_addc_u32 s1, s1, 0
	s_waitcnt lgkmcnt(0)
	v_mov_b32_e32 v29, v20
	v_mov_b32_e32 v20, v13
	s_cmp_eq_u32 s0, 0x600000
	s_waitcnt vmcnt(63)
	v_pk_fma_f32 v[8:9], v[30:31], v[28:29], v[8:9] op_sel_hi:[0,1,1]
	s_waitcnt vmcnt(62)
	v_pk_fma_f32 v[8:9], v[32:33], v[20:21], v[8:9] op_sel_hi:[0,1,1]
	v_mov_b32_e32 v20, v14
	v_mov_b32_e32 v21, v22
	v_mov_b32_e32 v22, v15
	s_waitcnt vmcnt(61)
	v_pk_fma_f32 v[8:9], v[34:35], v[20:21], v[8:9] op_sel_hi:[0,1,1]
	s_waitcnt vmcnt(60)
	v_pk_fma_f32 v[8:9], v[36:37], v[22:23], v[8:9] op_sel_hi:[0,1,1]
	v_mov_b32_e32 v22, v16
	ds_read_b128 v[12:15], v0 offset:4112
	v_add_u32_e32 v0, 32, v0
	s_waitcnt lgkmcnt(0)
	v_mov_b32_e32 v23, v12
	v_mov_b32_e32 v12, v17
	s_waitcnt vmcnt(59)
	v_pk_fma_f32 v[8:9], v[38:39], v[22:23], v[8:9] op_sel_hi:[0,1,1]
	s_waitcnt vmcnt(58)
	v_pk_fma_f32 v[8:9], v[40:41], v[12:13], v[8:9] op_sel_hi:[0,1,1]
	v_mov_b32_e32 v16, v18
	v_mov_b32_e32 v17, v14
	v_mov_b32_e32 v14, v19
	s_waitcnt vmcnt(57)
	v_pk_fma_f32 v[8:9], v[42:43], v[16:17], v[8:9] op_sel_hi:[0,1,1]
	s_waitcnt vmcnt(56)
	v_pk_fma_f32 v[8:9], v[44:45], v[14:15], v[8:9] op_sel_hi:[0,1,1]
	ds_read_b128 v[12:15], v0
	ds_read_b128 v[16:19], v0 offset:16
	ds_read_b128 v[20:23], v0 offset:4096
	s_mov_b32 s25, 0x2a000
	s_add_u32 s0, s0, 0x30000
	s_waitcnt lgkmcnt(2)
	v_mov_b32_e32 v28, v12
	s_addc_u32 s1, s1, 0
	s_waitcnt lgkmcnt(0)
	v_mov_b32_e32 v29, v20
	v_mov_b32_e32 v20, v13
	s_cmp_eq_u32 s0, 0x600000
	s_waitcnt vmcnt(55)
	v_pk_fma_f32 v[8:9], v[46:47], v[28:29], v[8:9] op_sel_hi:[0,1,1]
	s_waitcnt vmcnt(54)
	v_pk_fma_f32 v[8:9], v[48:49], v[20:21], v[8:9] op_sel_hi:[0,1,1]
	v_mov_b32_e32 v20, v14
	v_mov_b32_e32 v21, v22
	v_mov_b32_e32 v22, v15
	s_waitcnt vmcnt(53)
	v_pk_fma_f32 v[8:9], v[50:51], v[20:21], v[8:9] op_sel_hi:[0,1,1]
	s_waitcnt vmcnt(52)
	v_pk_fma_f32 v[8:9], v[52:53], v[22:23], v[8:9] op_sel_hi:[0,1,1]
	v_mov_b32_e32 v22, v16
	ds_read_b128 v[12:15], v0 offset:4112
	v_add_u32_e32 v0, 32, v0
	s_waitcnt lgkmcnt(0)
	v_mov_b32_e32 v23, v12
	v_mov_b32_e32 v12, v17
	s_waitcnt vmcnt(51)
	v_pk_fma_f32 v[8:9], v[54:55], v[22:23], v[8:9] op_sel_hi:[0,1,1]
	s_waitcnt vmcnt(50)
	v_pk_fma_f32 v[8:9], v[56:57], v[12:13], v[8:9] op_sel_hi:[0,1,1]
	v_mov_b32_e32 v16, v18
	v_mov_b32_e32 v17, v14
	v_mov_b32_e32 v14, v19
	s_waitcnt vmcnt(49)
	v_pk_fma_f32 v[8:9], v[58:59], v[16:17], v[8:9] op_sel_hi:[0,1,1]
	s_waitcnt vmcnt(48)
	v_pk_fma_f32 v[8:9], v[60:61], v[14:15], v[8:9] op_sel_hi:[0,1,1]
	ds_read_b128 v[12:15], v0
	ds_read_b128 v[16:19], v0 offset:16
	ds_read_b128 v[20:23], v0 offset:4096
	s_mov_b32 s25, 0x2a000
	s_add_u32 s0, s0, 0x30000
	s_waitcnt lgkmcnt(2)
; DI void ada_task(const Params& p, int task, char* smem) {
;     ...
;   const float* w = p.in[3] + ((size_t)l * 1024 + kq * 256) * 6144 + n0 + j;
;   float a0 = 0.f, a1 = 0.f;
; #pragma unroll 8
;   for (int k = 0; k < 256; ++k) { const float wv = w[(size_t)k * 6144]; a0 += sc[kq * 256 + k] * wv; a1 += sc[1024 + kq * 256 + k] * wv; }
	v_mov_b32_e32 v28, v12
	s_addc_u32 s1, s1, 0
	s_waitcnt lgkmcnt(0)
	v_mov_b32_e32 v29, v20
	v_mov_b32_e32 v20, v13
	s_cmp_eq_u32 s0, 0x600000
	s_waitcnt vmcnt(47)
	v_pk_fma_f32 v[8:9], v[62:63], v[28:29], v[8:9] op_sel_hi:[0,1,1]
	s_waitcnt vmcnt(46)
	v_pk_fma_f32 v[8:9], v[64:65], v[20:21], v[8:9] op_sel_hi:[0,1,1]
	v_mov_b32_e32 v20, v14
	v_mov_b32_e32 v21, v22
	v_mov_b32_e32 v22, v15
	s_waitcnt vmcnt(45)
	v_pk_fma_f32 v[8:9], v[66:67], v[20:21], v[8:9] op_sel_hi:[0,1,1]
	s_waitcnt vmcnt(44)
	v_pk_fma_f32 v[8:9], v[68:69], v[22:23], v[8:9] op_sel_hi:[0,1,1]
	v_mov_b32_e32 v22, v16
	ds_read_b128 v[12:15], v0 offset:4112
	v_add_u32_e32 v0, 32, v0
	s_waitcnt lgkmcnt(0)
	v_mov_b32_e32 v23, v12
	v_mov_b32_e32 v12, v17
	s_waitcnt vmcnt(43)
	v_pk_fma_f32 v[8:9], v[70:71], v[22:23], v[8:9] op_sel_hi:[0,1,1]
	s_waitcnt vmcnt(42)
	v_pk_fma_f32 v[8:9], v[72:73], v[12:13], v[8:9] op_sel_hi:[0,1,1]
	v_mov_b32_e32 v16, v18
	v_mov_b32_e32 v17, v14
	v_mov_b32_e32 v14, v19
	s_waitcnt vmcnt(41)
	v_pk_fma_f32 v[8:9], v[74:75], v[16:17], v[8:9] op_sel_hi:[0,1,1]
	s_waitcnt vmcnt(40)
	v_pk_fma_f32 v[8:9], v[76:77], v[14:15], v[8:9] op_sel_hi:[0,1,1]
	ds_read_b128 v[12:15], v0
	ds_read_b128 v[16:19], v0 offset:16
	ds_read_b128 v[20:23], v0 offset:4096
	s_mov_b32 s25, 0x2a000
	s_add_u32 s0, s0, 0x30000
	s_waitcnt lgkmcnt(2)
	v_mov_b32_e32 v28, v12
	s_addc_u32 s1, s1, 0
	s_waitcnt lgkmcnt(0)
	v_mov_b32_e32 v29, v20
	v_mov_b32_e32 v20, v13
	s_cmp_eq_u32 s0, 0x600000
	s_waitcnt vmcnt(39)
	v_pk_fma_f32 v[8:9], v[78:79], v[28:29], v[8:9] op_sel_hi:[0,1,1]
	s_waitcnt vmcnt(38)
	v_pk_fma_f32 v[8:9], v[80:81], v[20:21], v[8:9] op_sel_hi:[0,1,1]
	v_mov_b32_e32 v20, v14
	v_mov_b32_e32 v21, v22
	v_mov_b32_e32 v22, v15
	s_waitcnt vmcnt(37)
	v_pk_fma_f32 v[8:9], v[82:83], v[20:21], v[8:9] op_sel_hi:[0,1,1]
	s_waitcnt vmcnt(36)
	v_pk_fma_f32 v[8:9], v[84:85], v[22:23], v[8:9] op_sel_hi:[0,1,1]
	v_mov_b32_e32 v22, v16
	ds_read_b128 v[12:15], v0 offset:4112
	v_add_u32_e32 v0, 32, v0
	s_waitcnt lgkmcnt(0)
	v_mov_b32_e32 v23, v12
	v_mov_b32_e32 v12, v17
	s_waitcnt vmcnt(35)
	v_pk_fma_f32 v[8:9], v[86:87], v[22:23], v[8:9] op_sel_hi:[0,1,1]
	s_waitcnt vmcnt(34)
	v_pk_fma_f32 v[8:9], v[88:89], v[12:13], v[8:9] op_sel_hi:[0,1,1]
	v_mov_b32_e32 v16, v18
	v_mov_b32_e32 v17, v14
	v_mov_b32_e32 v14, v19
	s_waitcnt vmcnt(33)
	v_pk_fma_f32 v[8:9], v[90:91], v[16:17], v[8:9] op_sel_hi:[0,1,1]
	s_waitcnt vmcnt(32)
	v_pk_fma_f32 v[8:9], v[92:93], v[14:15], v[8:9] op_sel_hi:[0,1,1]
	ds_read_b128 v[12:15], v0
	ds_read_b128 v[16:19], v0 offset:16
	ds_read_b128 v[20:23], v0 offset:4096
	s_mov_b32 s25, 0x2a000
	s_add_u32 s0, s0, 0x30000
	s_waitcnt lgkmcnt(2)
	v_mov_b32_e32 v28, v12
	s_addc_u32 s1, s1, 0
	s_waitcnt lgkmcnt(0)
	v_mov_b32_e32 v29, v20
	v_mov_b32_e32 v20, v13
	s_cmp_eq_u32 s0, 0x600000
	s_waitcnt vmcnt(31)
	v_pk_fma_f32 v[8:9], v[94:95], v[28:29], v[8:9] op_sel_hi:[0,1,1]
	s_waitcnt vmcnt(30)
	v_pk_fma_f32 v[8:9], v[96:97], v[20:21], v[8:9] op_sel_hi:[0,1,1]
	v_mov_b32_e32 v20, v14
	v_mov_b32_e32 v21, v22
	v_mov_b32_e32 v22, v15
	s_waitcnt vmcnt(29)
	v_pk_fma_f32 v[8:9], v[98:99], v[20:21], v[8:9] op_sel_hi:[0,1,1]
	s_waitcnt vmcnt(28)
	v_pk_fma_f32 v[8:9], v[100:101], v[22:23], v[8:9] op_sel_hi:[0,1,1]
	v_mov_b32_e32 v22, v16
	ds_read_b128 v[12:15], v0 offset:4112
	v_add_u32_e32 v0, 32, v0
	s_waitcnt lgkmcnt(0)
	v_mov_b32_e32 v23, v12
	v_mov_b32_e32 v12, v17
	s_waitcnt vmcnt(27)
	v_pk_fma_f32 v[8:9], v[102:103], v[22:23], v[8:9] op_sel_hi:[0,1,1]
	s_waitcnt vmcnt(26)
	v_pk_fma_f32 v[8:9], v[104:105], v[12:13], v[8:9] op_sel_hi:[0,1,1]
	v_mov_b32_e32 v16, v18
	v_mov_b32_e32 v17, v14
	v_mov_b32_e32 v14, v19
	s_waitcnt vmcnt(25)
	v_pk_fma_f32 v[8:9], v[106:107], v[16:17], v[8:9] op_sel_hi:[0,1,1]
	s_waitcnt vmcnt(24)
	v_pk_fma_f32 v[8:9], v[108:109], v[14:15], v[8:9] op_sel_hi:[0,1,1]
	ds_read_b128 v[12:15], v0
	ds_read_b128 v[16:19], v0 offset:16
	ds_read_b128 v[20:23], v0 offset:4096
	s_mov_b32 s25, 0x2a000
	s_add_u32 s0, s0, 0x30000
	s_waitcnt lgkmcnt(2)
	v_mov_b32_e32 v28, v12
	s_addc_u32 s1, s1, 0
	s_waitcnt lgkmcnt(0)
	v_mov_b32_e32 v29, v20
	v_mov_b32_e32 v20, v13
	s_cmp_eq_u32 s0, 0x600000
	s_waitcnt vmcnt(23)
	v_pk_fma_f32 v[8:9], v[110:111], v[28:29], v[8:9] op_sel_hi:[0,1,1]
	s_waitcnt vmcnt(22)
	v_pk_fma_f32 v[8:9], v[112:113], v[20:21], v[8:9] op_sel_hi:[0,1,1]
	v_mov_b32_e32 v20, v14
	v_mov_b32_e32 v21, v22
	v_mov_b32_e32 v22, v15
	s_waitcnt vmcnt(21)
	v_pk_fma_f32 v[8:9], v[114:115], v[20:21], v[8:9] op_sel_hi:[0,1,1]
	s_waitcnt vmcnt(20)
	v_pk_fma_f32 v[8:9], v[116:117], v[22:23], v[8:9] op_sel_hi:[0,1,1]
	v_mov_b32_e32 v22, v16
	ds_read_b128 v[12:15], v0 offset:4112
	v_add_u32_e32 v0, 32, v0
	s_waitcnt lgkmcnt(0)
; DI void ada_task(const Params& p, int task, char* smem) {
;     ...
;   for (int k = 0; k < 256; ++k) { const float wv = w[(size_t)k * 6144]; a0 += sc[kq * 256 + k] * wv; a1 += sc[1024 + kq * 256 + k] * wv; }
;   red[(kq * 2 + 0) * 64 + j] = a0; red[(kq * 2 + 1) * 64 + j] = a1;
;   __syncthreads();
;   if (tid < 128) {
;     const int b = tid >> 6;
;     float s = red[(0 * 2 + b) * 64 + j] + red[(1 * 2 + b) * 64 + j] + red[(2 * 2 + b) * 64 + j] + red[(3 * 2 + b) * 64 + j];
;     ((float*)(p.ws + O_ADA))[((size_t)l * 2 + b) * 6144 + n0 + j] = s + p.in[4][(size_t)l * 6144 + n0 + j];
;   }
	v_mov_b32_e32 v23, v12
	v_mov_b32_e32 v12, v17
	s_waitcnt vmcnt(19)
	v_pk_fma_f32 v[8:9], v[118:119], v[22:23], v[8:9] op_sel_hi:[0,1,1]
	s_waitcnt vmcnt(18)
	v_pk_fma_f32 v[8:9], v[120:121], v[12:13], v[8:9] op_sel_hi:[0,1,1]
	v_mov_b32_e32 v16, v18
	v_mov_b32_e32 v17, v14
	v_mov_b32_e32 v14, v19
	s_waitcnt vmcnt(17)
	v_pk_fma_f32 v[8:9], v[122:123], v[16:17], v[8:9] op_sel_hi:[0,1,1]
	s_waitcnt vmcnt(16)
	v_pk_fma_f32 v[8:9], v[124:125], v[14:15], v[8:9] op_sel_hi:[0,1,1]
	ds_read_b128 v[12:15], v0
	ds_read_b128 v[16:19], v0 offset:16
	ds_read_b128 v[20:23], v0 offset:4096
	s_mov_b32 s25, 0x2a000
	s_add_u32 s0, s0, 0x30000
	s_waitcnt lgkmcnt(2)
	v_mov_b32_e32 v28, v12
	s_addc_u32 s1, s1, 0
	s_waitcnt lgkmcnt(0)
	v_mov_b32_e32 v29, v20
	v_mov_b32_e32 v20, v13
	s_cmp_eq_u32 s0, 0x600000
	s_waitcnt vmcnt(15)
	v_pk_fma_f32 v[8:9], v[126:127], v[28:29], v[8:9] op_sel_hi:[0,1,1]
	s_waitcnt vmcnt(14)
	v_pk_fma_f32 v[8:9], v[128:129], v[20:21], v[8:9] op_sel_hi:[0,1,1]
	v_mov_b32_e32 v20, v14
	v_mov_b32_e32 v21, v22
	v_mov_b32_e32 v22, v15
	s_waitcnt vmcnt(13)
	v_pk_fma_f32 v[8:9], v[130:131], v[20:21], v[8:9] op_sel_hi:[0,1,1]
	s_waitcnt vmcnt(12)
	v_pk_fma_f32 v[8:9], v[132:133], v[22:23], v[8:9] op_sel_hi:[0,1,1]
	v_mov_b32_e32 v22, v16
	ds_read_b128 v[12:15], v0 offset:4112
	v_add_u32_e32 v0, 32, v0
	s_waitcnt lgkmcnt(0)
	v_mov_b32_e32 v23, v12
	v_mov_b32_e32 v12, v17
	s_waitcnt vmcnt(11)
	v_pk_fma_f32 v[8:9], v[134:135], v[22:23], v[8:9] op_sel_hi:[0,1,1]
	s_waitcnt vmcnt(10)
	v_pk_fma_f32 v[8:9], v[136:137], v[12:13], v[8:9] op_sel_hi:[0,1,1]
	v_mov_b32_e32 v16, v18
	v_mov_b32_e32 v17, v14
	v_mov_b32_e32 v14, v19
	s_waitcnt vmcnt(9)
	v_pk_fma_f32 v[8:9], v[138:139], v[16:17], v[8:9] op_sel_hi:[0,1,1]
	s_waitcnt vmcnt(8)
	v_pk_fma_f32 v[8:9], v[140:141], v[14:15], v[8:9] op_sel_hi:[0,1,1]
	ds_read_b128 v[12:15], v0
	ds_read_b128 v[16:19], v0 offset:16
	ds_read_b128 v[20:23], v0 offset:4096
	s_mov_b32 s25, 0x2a000
	s_add_u32 s0, s0, 0x30000
	s_waitcnt lgkmcnt(2)
	v_mov_b32_e32 v28, v12
	s_addc_u32 s1, s1, 0
	s_waitcnt lgkmcnt(0)
	v_mov_b32_e32 v29, v20
	v_mov_b32_e32 v20, v13
	s_cmp_eq_u32 s0, 0x600000
	s_waitcnt vmcnt(7)
	v_pk_fma_f32 v[8:9], v[142:143], v[28:29], v[8:9] op_sel_hi:[0,1,1]
	s_waitcnt vmcnt(6)
	v_pk_fma_f32 v[8:9], v[144:145], v[20:21], v[8:9] op_sel_hi:[0,1,1]
	v_mov_b32_e32 v20, v14
	v_mov_b32_e32 v21, v22
	v_mov_b32_e32 v22, v15
	s_waitcnt vmcnt(5)
	v_pk_fma_f32 v[8:9], v[146:147], v[20:21], v[8:9] op_sel_hi:[0,1,1]
	s_waitcnt vmcnt(4)
	v_pk_fma_f32 v[8:9], v[148:149], v[22:23], v[8:9] op_sel_hi:[0,1,1]
	v_mov_b32_e32 v22, v16
	ds_read_b128 v[12:15], v0 offset:4112
	v_add_u32_e32 v0, 32, v0
	s_waitcnt lgkmcnt(0)
	v_mov_b32_e32 v23, v12
	v_mov_b32_e32 v12, v17
	s_waitcnt vmcnt(3)
	v_pk_fma_f32 v[8:9], v[150:151], v[22:23], v[8:9] op_sel_hi:[0,1,1]
	s_waitcnt vmcnt(2)
	v_pk_fma_f32 v[8:9], v[152:153], v[12:13], v[8:9] op_sel_hi:[0,1,1]
	v_mov_b32_e32 v16, v18
	v_mov_b32_e32 v17, v14
	v_mov_b32_e32 v14, v19
	s_waitcnt vmcnt(1)
	v_pk_fma_f32 v[8:9], v[154:155], v[16:17], v[8:9] op_sel_hi:[0,1,1]
	s_waitcnt vmcnt(0)
	v_pk_fma_f32 v[8:9], v[156:157], v[14:15], v[8:9] op_sel_hi:[0,1,1]
	s_cbranch_scc0 .LBB0_55
	v_lshlrev_b32_e32 v0, 2, v4
	v_lshl_or_b32 v4, v3, 9, v0
	v_cmp_gt_i32_e32 vcc, s31, v2
	ds_write2st64_b32 v4, v8, v9 offset0:32 offset1:33
	s_waitcnt lgkmcnt(0)
	s_barrier
	s_and_saveexec_b64 s[0:1], vcc
	s_cbranch_execz .LBB0_58
	v_and_b32_e32 v2, 0x3fffffc0, v2
	v_lshl_or_b32 v2, v2, 2, v0
	ds_read_b32 v6, v10 offset:8192
	ds_read2st64_b32 v[4:5], v2 offset0:34 offset1:36
	v_readlane_b32 s44, v246, 1
	ds_read_b32 v2, v2 offset:9728
	s_mul_i32 s25, s9, 0x6000
	v_readlane_b32 s52, v246, 9
	v_readlane_b32 s53, v246, 10
	s_add_u32 s25, s52, s25
	s_addc_u32 s26, s53, 0
	s_lshl_b32 s90, s24, 2
	s_waitcnt lgkmcnt(1)
	v_add_f32_e32 v4, v6, v4
	s_add_u32 s24, s25, s90
	v_add_f32_e32 v4, v4, v5
	s_addc_u32 s25, s26, 0
	s_waitcnt lgkmcnt(0)
	v_add_f32_e32 v2, v4, v2
	global_load_dword v4, v0, s[24:25]
	v_readlane_b32 s24, v246, 37
	v_readlane_b32 s25, v246, 38
	v_lshl_add_u32 v5, s9, 1, v3
	s_movk_i32 s9, 0x6000
	v_readlane_b32 s45, v246, 2
	v_readlane_b32 s46, v246, 3
	v_readlane_b32 s47, v246, 4
	v_readlane_b32 s48, v246, 5
	v_readlane_b32 s49, v246, 6
	v_readlane_b32 s50, v246, 7
	v_readlane_b32 s51, v246, 8
	v_readlane_b32 s54, v246, 11
	v_readlane_b32 s55, v246, 12
	v_readlane_b32 s56, v246, 13
	v_readlane_b32 s57, v246, 14
	v_readlane_b32 s58, v246, 15
	v_readlane_b32 s59, v246, 16
	s_waitcnt vmcnt(0)
	v_add_f32_e32 v4, v2, v4
	v_mov_b64_e32 v[2:3], s[24:25]
	v_mad_i64_i32 v[2:3], s[24:25], v5, s9, v[2:3]
	v_lshl_add_u64 v[2:3], v[2:3], 0, s[90:91]
	v_lshl_add_u64 v[2:3], v[2:3], 0, v[0:1]
	global_store_dword v[2:3], v4, off

; #define MFMA32(a, b, c) __builtin_amdgcn_mfma_f32_32x32x16_bf16((a), (b), (c), 0, 0, 0)
; DI unsigned pk2(float a, float b) { f32x2 v = {a, b}; bf2_t r = __builtin_convertvector(v, bf2_t); return __builtin_bit_cast(unsigned, r); }
; DI float bf_lo(unsigned u) { return __uint_as_float(u << 16); }
; DI float bf_hi(unsigned u) { return __uint_as_float(u & 0xffff0000u); }
; DI void cmp_tile(const Params& p, int l, int tile, char* smem) {
;     ...
;   const bf16_t* brow = W1T + (size_t)r * 2048 + half * 8;
; #pragma unroll 2
;   for (int t8 = 0; t8 < 8; ++t8) {
;     const int tl = 8 * w + t8;
; #pragma unroll
;     for (int dk = 0; dk < 4; ++dk) {
;       const uint4 av = *(const uint4*)(arow + (size_t)tl * 128 + dk * 16);
;       const float4 p0 = *(const float4*)(pe + tl * 64 + dk * 16 + half * 8);
;       const float4 p1 = *(const float4*)(pe + tl * 64 + dk * 16 + half * 8 + 4);
;       uint4 a2;
;       a2.x = pk2(bf_lo(av.x) + p0.x, bf_hi(av.x) + p0.y);
;       a2.y = pk2(bf_lo(av.y) + p0.z, bf_hi(av.y) + p0.w);
;       a2.z = pk2(bf_lo(av.z) + p1.x, bf_hi(av.z) + p1.y);
;       a2.w = pk2(bf_lo(av.w) + p1.z, bf_hi(av.w) + p1.w);
;       const bf16x8 a8 = __builtin_bit_cast(bf16x8, a2);
; #pragma unroll
;       for (int nf = 0; nf < 4; ++nf) {
;         const bf16x8 bv = *(const bf16x8*)(brow + (size_t)(nf * 32) * 2048 + tl * 64 + dk * 16);
;         acc[nf] = MFMA32(a8, bv, acc[nf]);
;       }
;     }
;   }
.LBB0_541:
	v_lshl_add_u64 v[68:69], v[76:77], 0, v[0:1]
	v_lshl_add_u64 v[66:67], v[74:75], 0, s[42:43]
	v_lshl_add_u64 v[84:85], v[72:73], 0, v[0:1]
	v_add_co_u32_e32 v82, vcc, s35, v84
	s_nop 1
	v_addc_co_u32_e32 v83, vcc, 0, v85, vcc
	v_add_co_u32_e32 v78, vcc, s41, v84
	s_nop 1
	v_addc_co_u32_e32 v79, vcc, 0, v85, vcc
	v_add_co_u32_e32 v80, vcc, s15, v84
	s_nop 1
	v_addc_co_u32_e32 v81, vcc, 0, v85, vcc
	global_load_dwordx4 v[104:107], v[68:69], off
	global_load_dwordx4 v[108:111], v[66:67], off
	global_load_dwordx4 v[112:115], v[66:67], off offset:16
	global_load_dwordx4 v[116:119], v[84:85], off
	global_load_dwordx4 v[120:123], v[82:83], off
	global_load_dwordx4 v[124:127], v[78:79], off
	global_load_dwordx4 v[128:131], v[80:81], off
	global_load_dwordx4 v[132:135], v[68:69], off offset:32
	global_load_dwordx4 v[136:139], v[66:67], off offset:64
	global_load_dwordx4 v[140:143], v[66:67], off offset:80
	global_load_dwordx4 v[144:147], v[84:85], off offset:32
	global_load_dwordx4 v[148:151], v[82:83], off offset:32
	global_load_dwordx4 v[152:155], v[78:79], off offset:32
	global_load_dwordx4 v[156:159], v[80:81], off offset:32
	s_waitcnt vmcnt(11)
	v_lshlrev_b32_e32 v164, 16, v104
	v_and_b32_e32 v165, 0xffff0000, v104
	v_pk_add_f32 v[164:165], v[108:109], v[164:165]
	v_cvt_pk_bf16_f32 v160, v164, v165
	v_lshlrev_b32_e32 v164, 16, v105
	v_and_b32_e32 v165, 0xffff0000, v105
	v_pk_add_f32 v[164:165], v[110:111], v[164:165]
	v_cvt_pk_bf16_f32 v161, v164, v165
	v_lshlrev_b32_e32 v164, 16, v106
	v_and_b32_e32 v165, 0xffff0000, v106
	v_pk_add_f32 v[164:165], v[112:113], v[164:165]
	v_cvt_pk_bf16_f32 v162, v164, v165
	v_lshlrev_b32_e32 v164, 16, v107
	v_and_b32_e32 v165, 0xffff0000, v107
	v_pk_add_f32 v[164:165], v[114:115], v[164:165]
	v_cvt_pk_bf16_f32 v163, v164, v165
	s_waitcnt vmcnt(10)
	s_nop 1
	v_mfma_f32_32x32x16_bf16 v[2:17], v[160:163], v[116:119], v[2:17]
	s_waitcnt vmcnt(9)
	v_mfma_f32_32x32x16_bf16 v[18:33], v[160:163], v[120:123], v[18:33]
	s_waitcnt vmcnt(8)
	v_mfma_f32_32x32x16_bf16 v[34:49], v[160:163], v[124:127], v[34:49]
	s_waitcnt vmcnt(7)
	v_mfma_f32_32x32x16_bf16 v[50:65], v[160:163], v[128:131], v[50:65]
	global_load_dwordx4 v[104:107], v[68:69], off offset:64
	global_load_dwordx4 v[108:111], v[66:67], off offset:128
	global_load_dwordx4 v[112:115], v[66:67], off offset:144
	global_load_dwordx4 v[116:119], v[84:85], off offset:64
	global_load_dwordx4 v[120:123], v[82:83], off offset:64
	global_load_dwordx4 v[124:127], v[78:79], off offset:64
	global_load_dwordx4 v[128:131], v[80:81], off offset:64
	s_waitcnt vmcnt(11)
	v_lshlrev_b32_e32 v164, 16, v132
	v_and_b32_e32 v165, 0xffff0000, v132
	v_pk_add_f32 v[164:165], v[136:137], v[164:165]
	v_cvt_pk_bf16_f32 v160, v164, v165
	v_lshlrev_b32_e32 v164, 16, v133
	v_and_b32_e32 v165, 0xffff0000, v133
	v_pk_add_f32 v[164:165], v[138:139], v[164:165]
	v_cvt_pk_bf16_f32 v161, v164, v165
	v_lshlrev_b32_e32 v164, 16, v134
	v_and_b32_e32 v165, 0xffff0000, v134
	v_pk_add_f32 v[164:165], v[140:141], v[164:165]
	v_cvt_pk_bf16_f32 v162, v164, v165
	v_lshlrev_b32_e32 v164, 16, v135
	v_and_b32_e32 v165, 0xffff0000, v135
	v_pk_add_f32 v[164:165], v[142:143], v[164:165]
	v_cvt_pk_bf16_f32 v163, v164, v165
	s_waitcnt vmcnt(10)
	s_nop 1
	v_mfma_f32_32x32x16_bf16 v[2:17], v[160:163], v[144:147], v[2:17]
	s_waitcnt vmcnt(9)
	v_mfma_f32_32x32x16_bf16 v[18:33], v[160:163], v[148:151], v[18:33]
	s_waitcnt vmcnt(8)
	v_mfma_f32_32x32x16_bf16 v[34:49], v[160:163], v[152:155], v[34:49]
	s_waitcnt vmcnt(7)
	v_mfma_f32_32x32x16_bf16 v[50:65], v[160:163], v[156:159], v[50:65]
	global_load_dwordx4 v[132:135], v[68:69], off offset:96
	global_load_dwordx4 v[136:139], v[66:67], off offset:192
	global_load_dwordx4 v[140:143], v[66:67], off offset:208
	global_load_dwordx4 v[144:147], v[84:85], off offset:96
	global_load_dwordx4 v[148:151], v[82:83], off offset:96
	global_load_dwordx4 v[152:155], v[78:79], off offset:96
	global_load_dwordx4 v[156:159], v[80:81], off offset:96
	s_waitcnt vmcnt(11)
	v_lshlrev_b32_e32 v164, 16, v104
	v_and_b32_e32 v165, 0xffff0000, v104
	v_pk_add_f32 v[164:165], v[108:109], v[164:165]
	v_cvt_pk_bf16_f32 v160, v164, v165
	v_lshlrev_b32_e32 v164, 16, v105
	v_and_b32_e32 v165, 0xffff0000, v105
	v_pk_add_f32 v[164:165], v[110:111], v[164:165]
	v_cvt_pk_bf16_f32 v161, v164, v165
	v_lshlrev_b32_e32 v164, 16, v106
	v_and_b32_e32 v165, 0xffff0000, v106
	v_pk_add_f32 v[164:165], v[112:113], v[164:165]
	v_cvt_pk_bf16_f32 v162, v164, v165
	v_lshlrev_b32_e32 v164, 16, v107
	v_and_b32_e32 v165, 0xffff0000, v107
	v_pk_add_f32 v[164:165], v[114:115], v[164:165]
	v_cvt_pk_bf16_f32 v163, v164, v165
	s_waitcnt vmcnt(10)
	s_nop 1
	v_mfma_f32_32x32x16_bf16 v[2:17], v[160:163], v[116:119], v[2:17]
	s_waitcnt vmcnt(9)
	v_mfma_f32_32x32x16_bf16 v[18:33], v[160:163], v[120:123], v[18:33]
	s_waitcnt vmcnt(8)
	v_mfma_f32_32x32x16_bf16 v[34:49], v[160:163], v[124:127], v[34:49]
	s_waitcnt vmcnt(7)
	v_mfma_f32_32x32x16_bf16 v[50:65], v[160:163], v[128:131], v[50:65]
	global_load_dwordx4 v[104:107], v[68:69], off offset:256
	global_load_dwordx4 v[108:111], v[66:67], off offset:256
	global_load_dwordx4 v[112:115], v[66:67], off offset:272
	global_load_dwordx4 v[116:119], v[84:85], off offset:128
	global_load_dwordx4 v[120:123], v[82:83], off offset:128
	global_load_dwordx4 v[124:127], v[78:79], off offset:128
	global_load_dwordx4 v[128:131], v[80:81], off offset:128
	s_waitcnt vmcnt(11)
; #define MFMA32(a, b, c) __builtin_amdgcn_mfma_f32_32x32x16_bf16((a), (b), (c), 0, 0, 0)
; DI unsigned pk2(float a, float b) { f32x2 v = {a, b}; bf2_t r = __builtin_convertvector(v, bf2_t); return __builtin_bit_cast(unsigned, r); }
; DI float bf_lo(unsigned u) { return __uint_as_float(u << 16); }
; DI float bf_hi(unsigned u) { return __uint_as_float(u & 0xffff0000u); }
; DI void cmp_tile(const Params& p, int l, int tile, char* smem) {
;     ...
;   const bf16_t* brow = W1T + (size_t)r * 2048 + half * 8;
; #pragma unroll 2
;   for (int t8 = 0; t8 < 8; ++t8) {
;     const int tl = 8 * w + t8;
; #pragma unroll
;     for (int dk = 0; dk < 4; ++dk) {
;       const uint4 av = *(const uint4*)(arow + (size_t)tl * 128 + dk * 16);
;       const float4 p0 = *(const float4*)(pe + tl * 64 + dk * 16 + half * 8);
;       const float4 p1 = *(const float4*)(pe + tl * 64 + dk * 16 + half * 8 + 4);
;       uint4 a2;
;       a2.x = pk2(bf_lo(av.x) + p0.x, bf_hi(av.x) + p0.y);
;       a2.y = pk2(bf_lo(av.y) + p0.z, bf_hi(av.y) + p0.w);
;       a2.z = pk2(bf_lo(av.z) + p1.x, bf_hi(av.z) + p1.y);
;       a2.w = pk2(bf_lo(av.w) + p1.z, bf_hi(av.w) + p1.w);
;       const bf16x8 a8 = __builtin_bit_cast(bf16x8, a2);
; #pragma unroll
;       for (int nf = 0; nf < 4; ++nf) {
;         const bf16x8 bv = *(const bf16x8*)(brow + (size_t)(nf * 32) * 2048 + tl * 64 + dk * 16);
;         acc[nf] = MFMA32(a8, bv, acc[nf]);
;       }
;     }
;   }
	v_lshlrev_b32_e32 v164, 16, v132
	v_and_b32_e32 v165, 0xffff0000, v132
	v_pk_add_f32 v[164:165], v[136:137], v[164:165]
	v_cvt_pk_bf16_f32 v160, v164, v165
	v_lshlrev_b32_e32 v164, 16, v133
	v_and_b32_e32 v165, 0xffff0000, v133
	v_pk_add_f32 v[164:165], v[138:139], v[164:165]
	v_cvt_pk_bf16_f32 v161, v164, v165
	v_lshlrev_b32_e32 v164, 16, v134
	v_and_b32_e32 v165, 0xffff0000, v134
	v_pk_add_f32 v[164:165], v[140:141], v[164:165]
	v_cvt_pk_bf16_f32 v162, v164, v165
	v_lshlrev_b32_e32 v164, 16, v135
	v_and_b32_e32 v165, 0xffff0000, v135
	v_pk_add_f32 v[164:165], v[142:143], v[164:165]
	v_cvt_pk_bf16_f32 v163, v164, v165
	s_waitcnt vmcnt(10)
	s_nop 1
	v_mfma_f32_32x32x16_bf16 v[2:17], v[160:163], v[144:147], v[2:17]
	s_waitcnt vmcnt(9)
	v_mfma_f32_32x32x16_bf16 v[18:33], v[160:163], v[148:151], v[18:33]
	s_waitcnt vmcnt(8)
	v_mfma_f32_32x32x16_bf16 v[34:49], v[160:163], v[152:155], v[34:49]
	s_waitcnt vmcnt(7)
	v_mfma_f32_32x32x16_bf16 v[50:65], v[160:163], v[156:159], v[50:65]
	global_load_dwordx4 v[132:135], v[68:69], off offset:288
	global_load_dwordx4 v[136:139], v[66:67], off offset:320
	global_load_dwordx4 v[140:143], v[66:67], off offset:336
	global_load_dwordx4 v[144:147], v[84:85], off offset:160
	global_load_dwordx4 v[148:151], v[82:83], off offset:160
	global_load_dwordx4 v[152:155], v[78:79], off offset:160
	global_load_dwordx4 v[156:159], v[80:81], off offset:160
	s_waitcnt vmcnt(11)
	v_lshlrev_b32_e32 v164, 16, v104
	v_and_b32_e32 v165, 0xffff0000, v104
	v_pk_add_f32 v[164:165], v[108:109], v[164:165]
	v_cvt_pk_bf16_f32 v160, v164, v165
	v_lshlrev_b32_e32 v164, 16, v105
	v_and_b32_e32 v165, 0xffff0000, v105
	v_pk_add_f32 v[164:165], v[110:111], v[164:165]
	v_cvt_pk_bf16_f32 v161, v164, v165
	v_lshlrev_b32_e32 v164, 16, v106
	v_and_b32_e32 v165, 0xffff0000, v106
	v_pk_add_f32 v[164:165], v[112:113], v[164:165]
	v_cvt_pk_bf16_f32 v162, v164, v165
	v_lshlrev_b32_e32 v164, 16, v107
	v_and_b32_e32 v165, 0xffff0000, v107
	v_pk_add_f32 v[164:165], v[114:115], v[164:165]
	v_cvt_pk_bf16_f32 v163, v164, v165
	s_waitcnt vmcnt(10)
	s_nop 1
	v_mfma_f32_32x32x16_bf16 v[2:17], v[160:163], v[116:119], v[2:17]
	s_waitcnt vmcnt(9)
	v_mfma_f32_32x32x16_bf16 v[18:33], v[160:163], v[120:123], v[18:33]
	s_waitcnt vmcnt(8)
	v_mfma_f32_32x32x16_bf16 v[34:49], v[160:163], v[124:127], v[34:49]
	s_waitcnt vmcnt(7)
	v_mfma_f32_32x32x16_bf16 v[50:65], v[160:163], v[128:131], v[50:65]
	global_load_dwordx4 v[104:107], v[68:69], off offset:320
	global_load_dwordx4 v[108:111], v[66:67], off offset:384
	global_load_dwordx4 v[112:115], v[66:67], off offset:400
	global_load_dwordx4 v[116:119], v[84:85], off offset:192
	global_load_dwordx4 v[120:123], v[82:83], off offset:192
	global_load_dwordx4 v[124:127], v[78:79], off offset:192
	global_load_dwordx4 v[128:131], v[80:81], off offset:192
	s_waitcnt vmcnt(11)
	v_lshlrev_b32_e32 v164, 16, v132
	v_and_b32_e32 v165, 0xffff0000, v132
	v_pk_add_f32 v[164:165], v[136:137], v[164:165]
	v_cvt_pk_bf16_f32 v160, v164, v165
	v_lshlrev_b32_e32 v164, 16, v133
	v_and_b32_e32 v165, 0xffff0000, v133
	v_pk_add_f32 v[164:165], v[138:139], v[164:165]
	v_cvt_pk_bf16_f32 v161, v164, v165
	v_lshlrev_b32_e32 v164, 16, v134
	v_and_b32_e32 v165, 0xffff0000, v134
	v_pk_add_f32 v[164:165], v[140:141], v[164:165]
	v_cvt_pk_bf16_f32 v162, v164, v165
	v_lshlrev_b32_e32 v164, 16, v135
	v_and_b32_e32 v165, 0xffff0000, v135
	v_pk_add_f32 v[164:165], v[142:143], v[164:165]
	v_cvt_pk_bf16_f32 v163, v164, v165
	s_waitcnt vmcnt(10)
	s_nop 1
	v_mfma_f32_32x32x16_bf16 v[2:17], v[160:163], v[144:147], v[2:17]
	s_waitcnt vmcnt(9)
	v_mfma_f32_32x32x16_bf16 v[18:33], v[160:163], v[148:151], v[18:33]
	s_waitcnt vmcnt(8)
	v_mfma_f32_32x32x16_bf16 v[34:49], v[160:163], v[152:155], v[34:49]
	s_waitcnt vmcnt(7)
	v_mfma_f32_32x32x16_bf16 v[50:65], v[160:163], v[156:159], v[50:65]
	global_load_dwordx4 v[132:135], v[68:69], off offset:352
	global_load_dwordx4 v[136:139], v[66:67], off offset:448
	global_load_dwordx4 v[140:143], v[66:67], off offset:464
	global_load_dwordx4 v[144:147], v[84:85], off offset:224
	global_load_dwordx4 v[148:151], v[82:83], off offset:224
	global_load_dwordx4 v[152:155], v[78:79], off offset:224
	global_load_dwordx4 v[156:159], v[80:81], off offset:224
	s_waitcnt vmcnt(11)
	v_lshlrev_b32_e32 v164, 16, v104
	v_and_b32_e32 v165, 0xffff0000, v104
	v_pk_add_f32 v[164:165], v[108:109], v[164:165]
	v_cvt_pk_bf16_f32 v160, v164, v165
	v_lshlrev_b32_e32 v164, 16, v105
	v_and_b32_e32 v165, 0xffff0000, v105
	v_pk_add_f32 v[164:165], v[110:111], v[164:165]
	v_cvt_pk_bf16_f32 v161, v164, v165
	v_lshlrev_b32_e32 v164, 16, v106
	v_and_b32_e32 v165, 0xffff0000, v106
	v_pk_add_f32 v[164:165], v[112:113], v[164:165]
	v_cvt_pk_bf16_f32 v162, v164, v165
	v_lshlrev_b32_e32 v164, 16, v107
	v_and_b32_e32 v165, 0xffff0000, v107
	v_pk_add_f32 v[164:165], v[114:115], v[164:165]
	v_cvt_pk_bf16_f32 v163, v164, v165
	s_waitcnt vmcnt(10)
	s_nop 1
	v_mfma_f32_32x32x16_bf16 v[2:17], v[160:163], v[116:119], v[2:17]
	s_waitcnt vmcnt(9)
	v_mfma_f32_32x32x16_bf16 v[18:33], v[160:163], v[120:123], v[18:33]
	s_waitcnt vmcnt(8)
	v_mfma_f32_32x32x16_bf16 v[34:49], v[160:163], v[124:127], v[34:49]
	s_waitcnt vmcnt(7)
	v_mfma_f32_32x32x16_bf16 v[50:65], v[160:163], v[128:131], v[50:65]
	s_waitcnt vmcnt(4)
	v_lshlrev_b32_e32 v164, 16, v132
	v_and_b32_e32 v165, 0xffff0000, v132
	v_pk_add_f32 v[164:165], v[136:137], v[164:165]
	v_cvt_pk_bf16_f32 v160, v164, v165
	v_lshlrev_b32_e32 v164, 16, v133
	v_and_b32_e32 v165, 0xffff0000, v133
	v_pk_add_f32 v[164:165], v[138:139], v[164:165]
	v_cvt_pk_bf16_f32 v161, v164, v165
	v_lshlrev_b32_e32 v164, 16, v134
	v_and_b32_e32 v165, 0xffff0000, v134
	v_pk_add_f32 v[164:165], v[140:141], v[164:165]
	v_cvt_pk_bf16_f32 v162, v164, v165
	v_lshlrev_b32_e32 v164, 16, v135
	v_and_b32_e32 v165, 0xffff0000, v135
	v_pk_add_f32 v[164:165], v[142:143], v[164:165]
	v_cvt_pk_bf16_f32 v163, v164, v165
	s_waitcnt vmcnt(3)
	s_nop 1
	v_mfma_f32_32x32x16_bf16 v[2:17], v[160:163], v[144:147], v[2:17]
	s_waitcnt vmcnt(2)
	v_mfma_f32_32x32x16_bf16 v[18:33], v[160:163], v[148:151], v[18:33]
	s_waitcnt vmcnt(1)
	v_mfma_f32_32x32x16_bf16 v[34:49], v[160:163], v[152:155], v[34:49]
	s_waitcnt vmcnt(0)
	v_mfma_f32_32x32x16_bf16 v[50:65], v[160:163], v[156:159], v[50:65]
	s_mov_b64 s[48:49], 0x200
	v_lshl_add_u64 v[72:73], v[72:73], 0, s[10:11]
	v_lshl_add_u64 v[76:77], v[76:77], 0, s[48:49]
	s_add_u32 s42, s42, 0x200
	s_addc_u32 s43, s43, 0
	s_cmpk_eq_i32 s42, 0x800
	s_cbranch_scc0 .LBB0_541
; DI int crow(int i, int h) { return (i & 3) + 8 * (i >> 2) + 4 * h; }
; DI float gelu_tanh(float x) {
;   const float u = 0.7978845608028654f * (x + 0.044715f * x * x * x);
;   const float e = __expf(2.f * u);
;   const float th = 1.f - 2.f / (e + 1.f);
;   return 0.5f * x * (1.f + th);
; }
; DI void cmp_tile(const Params& p, int l, int tile, char* smem) {
;     ...
;   __syncthreads();
; #pragma unroll
;   for (int nf = 0; nf < 4; ++nf)
; #pragma unroll
;     for (int i = 0; i < 16; ++i) part[w][crow(i, half)][nf * 32 + r] = acc[nf][i];
;   __syncthreads();
;   float hv[16];
; #pragma unroll
;   for (int e = 0; e < 16; ++e) {
;     const int idx = tid + 256 * e, row = idx >> 7, col = idx & 127;
;     hv[e] = gelu_tanh((part[0][row][col] + part[1][row][col]) + (part[2][row][col] + part[3][row][col]));
;   }
	v_bfe_u32 v66, v86, 5, 1
	v_lshlrev_b32_e32 v0, 14, v87
	v_lshlrev_b32_e32 v68, 11, v66
	v_lshlrev_b32_e32 v67, 2, v88
	v_or3_b32 v0, v0, v68, v67
	s_barrier
	s_nop 0
	ds_write2_b32 v0, v2, v18 offset1:32
	ds_write2_b32 v0, v3, v19 offset0:128 offset1:160
	v_add_u32_e32 v2, 0x400, v0
	ds_write2_b32 v2, v4, v20 offset1:32
	ds_write2_b32 v2, v5, v21 offset0:128 offset1:160
	v_add_u32_e32 v3, 0x1000, v0
	v_add_u32_e32 v4, 0x1400, v0
	ds_write2_b32 v3, v6, v22 offset1:32
	ds_write2_b32 v3, v7, v23 offset0:128 offset1:160
	ds_write2_b32 v4, v8, v24 offset1:32
	ds_write2_b32 v4, v9, v25 offset0:128 offset1:160
	v_add_u32_e32 v5, 0x2000, v0
	v_add_u32_e32 v6, 0x2400, v0
	v_add_u32_e32 v7, 0x3000, v0
	v_add_u32_e32 v8, 0x3400, v0
	ds_write2_b32 v5, v10, v26 offset1:32
	ds_write2_b32 v5, v11, v27 offset0:128 offset1:160
	ds_write2_b32 v6, v12, v28 offset1:32
	ds_write2_b32 v6, v13, v29 offset0:128 offset1:160
	ds_write2_b32 v7, v14, v30 offset1:32
	ds_write2_b32 v7, v15, v31 offset0:128 offset1:160
	ds_write2_b32 v8, v16, v32 offset1:32
	ds_write2_b32 v8, v17, v33 offset0:128 offset1:160
	ds_write2_b32 v0, v34, v50 offset0:64 offset1:96
	ds_write2_b32 v0, v35, v51 offset0:192 offset1:224
	ds_write2_b32 v2, v36, v52 offset0:64 offset1:96
	ds_write2_b32 v2, v37, v53 offset0:192 offset1:224
	ds_write2_b32 v3, v38, v54 offset0:64 offset1:96
	ds_write2_b32 v3, v39, v55 offset0:192 offset1:224
	ds_write2_b32 v4, v40, v56 offset0:64 offset1:96
	ds_write2_b32 v4, v41, v57 offset0:192 offset1:224
	ds_write2_b32 v5, v42, v58 offset0:64 offset1:96
	ds_write2_b32 v5, v43, v59 offset0:192 offset1:224
	ds_write2_b32 v6, v44, v60 offset0:64 offset1:96
	ds_write2_b32 v6, v45, v61 offset0:192 offset1:224
	ds_write2_b32 v7, v46, v62 offset0:64 offset1:96
	ds_write2_b32 v7, v47, v63 offset0:192 offset1:224
	ds_write2_b32 v8, v48, v64 offset0:64 offset1:96
	ds_write2_b32 v8, v49, v65 offset0:192 offset1:224
	v_and_b32_e32 v2, 0x7f, v86
	v_lshlrev_b32_e32 v4, 2, v2
	v_ashrrev_i32_e32 v0, 7, v86
	v_lshl_or_b32 v3, v0, 9, v4
	s_waitcnt lgkmcnt(0)
	s_barrier
	ds_read2st64_b32 v[6:7], v3 offset1:64
	ds_read2st64_b32 v[8:9], v3 offset0:128 offset1:192
	v_lshlrev_b32_e32 v2, 1, v2
	s_movk_i32 s9, 0x110
	s_movk_i32 s51, 0x110
	s_waitcnt lgkmcnt(1)
	v_add_f32_e32 v3, v6, v7
	s_waitcnt lgkmcnt(0)
	v_add_f32_e32 v5, v8, v9
	v_add_f32_e32 v5, v3, v5
	v_mul_f32_e32 v3, 0x3d372713, v5
	v_mul_f32_e32 v3, v5, v3
	v_fma_f32 v3, v5, v3, v5
	v_mul_f32_e32 v3, 0x3f4c422a, v3
	v_add_f32_e32 v3, v3, v3
	v_mul_f32_e32 v3, 0x3fb8aa3b, v3
	v_exp_f32_e32 v3, v3
	v_mul_f32_e32 v5, 0.5, v5
	v_add_f32_e32 v10, 1.0, v3
	v_div_scale_f32 v11, s[42:43], v10, v10, 2.0
	v_rcp_f32_e32 v12, v11
	v_div_scale_f32 v13, vcc, 2.0, v10, 2.0
	v_fma_f32 v3, -v11, v12, 1.0
	v_fmac_f32_e32 v12, v3, v12
	v_add_u32_e32 v3, 0x100, v86
	v_ashrrev_i32_e32 v3, 7, v3
	v_lshl_or_b32 v8, v3, 9, v4
	ds_read2st64_b32 v[6:7], v8 offset1:64
	ds_read2st64_b32 v[8:9], v8 offset0:128 offset1:192
	v_mul_f32_e32 v14, v13, v12
	v_fma_f32 v15, -v11, v14, v13
	v_fmac_f32_e32 v14, v15, v12
	s_waitcnt lgkmcnt(1)
	v_add_f32_e32 v6, v6, v7
	s_waitcnt lgkmcnt(0)
	v_add_f32_e32 v7, v8, v9
	v_add_f32_e32 v7, v6, v7
	v_mul_f32_e32 v6, 0x3d372713, v7
	v_mul_f32_e32 v6, v7, v6
	v_fma_f32 v6, v7, v6, v7
	v_mul_f32_e32 v6, 0x3f4c422a, v6
	v_add_f32_e32 v6, v6, v6
	v_mul_f32_e32 v6, 0x3fb8aa3b, v6
	v_exp_f32_e32 v6, v6
	v_fma_f32 v11, -v11, v14, v13
	v_div_fmas_f32 v8, v11, v12, v14
	v_div_fixup_f32 v8, v8, v10, 2.0
	v_add_f32_e32 v12, 1.0, v6
	v_div_scale_f32 v13, s[42:43], v12, v12, 2.0
	v_rcp_f32_e32 v14, v13
	v_sub_f32_e32 v8, 1.0, v8
	v_add_f32_e32 v6, 1.0, v8
	v_mul_f32_e32 v5, v5, v6
	v_fma_f32 v6, -v13, v14, 1.0
	v_fmac_f32_e32 v14, v6, v14
	v_add_u32_e32 v6, 0x200, v86
	v_ashrrev_i32_e32 v6, 7, v6
	v_lshl_or_b32 v10, v6, 9, v4
	ds_read2st64_b32 v[8:9], v10 offset1:64
	ds_read2st64_b32 v[10:11], v10 offset0:128 offset1:192
	v_div_scale_f32 v15, vcc, 2.0, v12, 2.0
	v_mul_f32_e32 v16, v15, v14
	s_waitcnt lgkmcnt(1)
	v_add_f32_e32 v8, v8, v9
	s_waitcnt lgkmcnt(0)
	v_add_f32_e32 v9, v10, v11
	v_add_f32_e32 v9, v8, v9
	v_mul_f32_e32 v8, 0x3d372713, v9
	v_mul_f32_e32 v8, v9, v8
	v_fma_f32 v8, v9, v8, v9
	v_mul_f32_e32 v8, 0x3f4c422a, v8
	v_add_f32_e32 v8, v8, v8
	v_mul_f32_e32 v8, 0x3fb8aa3b, v8
	v_exp_f32_e32 v8, v8
	v_fma_f32 v17, -v13, v16, v15
	v_fmac_f32_e32 v16, v17, v14
	v_fma_f32 v13, -v13, v16, v15
	v_div_fmas_f32 v10, v13, v14, v16
	v_add_f32_e32 v14, 1.0, v8
	v_div_scale_f32 v15, s[42:43], v14, v14, 2.0
	v_rcp_f32_e32 v16, v15
	v_div_fixup_f32 v10, v10, v12, 2.0
	v_sub_f32_e32 v10, 1.0, v10
	v_mul_f32_e32 v7, 0.5, v7
	v_add_f32_e32 v8, 1.0, v10
	v_mul_f32_e32 v7, v7, v8
	v_fma_f32 v8, -v15, v16, 1.0
	v_fmac_f32_e32 v16, v8, v16
	v_add_u32_e32 v8, 0x300, v86
	v_ashrrev_i32_e32 v8, 7, v8
	v_lshl_or_b32 v12, v8, 9, v4
	ds_read2st64_b32 v[10:11], v12 offset1:64
	ds_read2st64_b32 v[12:13], v12 offset0:128 offset1:192
	v_div_scale_f32 v17, vcc, 2.0, v14, 2.0
	v_mul_f32_e32 v18, v17, v16
	s_waitcnt lgkmcnt(1)
	v_add_f32_e32 v10, v10, v11
	s_waitcnt lgkmcnt(0)
	v_add_f32_e32 v11, v12, v13
	v_add_f32_e32 v11, v10, v11
	v_mul_f32_e32 v10, 0x3d372713, v11
	v_mul_f32_e32 v10, v11, v10
	v_fma_f32 v10, v11, v10, v11
	v_mul_f32_e32 v10, 0x3f4c422a, v10
	v_add_f32_e32 v10, v10, v10
	v_mul_f32_e32 v10, 0x3fb8aa3b, v10
	v_exp_f32_e32 v10, v10
	v_fma_f32 v19, -v15, v18, v17
	v_fmac_f32_e32 v18, v19, v16
	v_fma_f32 v15, -v15, v18, v17
	v_div_fmas_f32 v12, v15, v16, v18
	v_add_f32_e32 v16, 1.0, v10
	v_div_scale_f32 v17, s[42:43], v16, v16, 2.0
	v_rcp_f32_e32 v18, v17
	v_div_fixup_f32 v12, v12, v14, 2.0
	v_sub_f32_e32 v12, 1.0, v12
	v_mul_f32_e32 v9, 0.5, v9
	v_add_f32_e32 v10, 1.0, v12
	v_mul_f32_e32 v9, v9, v10
	v_fma_f32 v10, -v17, v18, 1.0
	v_fmac_f32_e32 v18, v10, v18
	v_add_u32_e32 v10, 0x400, v86
	v_ashrrev_i32_e32 v10, 7, v10
	v_lshl_or_b32 v14, v10, 9, v4
	ds_read2st64_b32 v[12:13], v14 offset1:64
	ds_read2st64_b32 v[14:15], v14 offset0:128 offset1:192
	v_div_scale_f32 v19, vcc, 2.0, v16, 2.0
	v_mul_f32_e32 v20, v19, v18
	s_waitcnt lgkmcnt(1)
; DI float gelu_tanh(float x) {
;   const float u = 0.7978845608028654f * (x + 0.044715f * x * x * x);
;   const float e = __expf(2.f * u);
;   const float th = 1.f - 2.f / (e + 1.f);
;   return 0.5f * x * (1.f + th);
; }
; DI void cmp_tile(const Params& p, int l, int tile, char* smem) {
;     ...
;   float hv[16];
; #pragma unroll
;   for (int e = 0; e < 16; ++e) {
;     const int idx = tid + 256 * e, row = idx >> 7, col = idx & 127;
;     hv[e] = gelu_tanh((part[0][row][col] + part[1][row][col]) + (part[2][row][col] + part[3][row][col]));
;   }
	v_add_f32_e32 v12, v12, v13
	s_waitcnt lgkmcnt(0)
	v_add_f32_e32 v13, v14, v15
	v_add_f32_e32 v13, v12, v13
	v_mul_f32_e32 v12, 0x3d372713, v13
	v_mul_f32_e32 v12, v13, v12
	v_fma_f32 v12, v13, v12, v13
	v_mul_f32_e32 v12, 0x3f4c422a, v12
	v_add_f32_e32 v12, v12, v12
	v_mul_f32_e32 v12, 0x3fb8aa3b, v12
	v_exp_f32_e32 v12, v12
	v_fma_f32 v21, -v17, v20, v19
	v_fmac_f32_e32 v20, v21, v18
	v_fma_f32 v17, -v17, v20, v19
	v_div_fmas_f32 v14, v17, v18, v20
	v_add_f32_e32 v18, 1.0, v12
	v_div_scale_f32 v19, s[42:43], v18, v18, 2.0
	v_rcp_f32_e32 v20, v19
	v_div_fixup_f32 v14, v14, v16, 2.0
	v_sub_f32_e32 v14, 1.0, v14
	v_mul_f32_e32 v11, 0.5, v11
	v_add_f32_e32 v12, 1.0, v14
	v_mul_f32_e32 v11, v11, v12
	v_fma_f32 v12, -v19, v20, 1.0
	v_fmac_f32_e32 v20, v12, v20
	v_add_u32_e32 v12, 0x500, v86
	v_ashrrev_i32_e32 v12, 7, v12
	v_lshl_or_b32 v16, v12, 9, v4
	ds_read2st64_b32 v[14:15], v16 offset1:64
	ds_read2st64_b32 v[16:17], v16 offset0:128 offset1:192
	v_div_scale_f32 v21, vcc, 2.0, v18, 2.0
	v_mul_f32_e32 v22, v21, v20
	v_fma_f32 v23, -v19, v22, v21
	v_fmac_f32_e32 v22, v23, v20
	s_waitcnt lgkmcnt(1)
	v_add_f32_e32 v14, v14, v15
	s_waitcnt lgkmcnt(0)
	v_add_f32_e32 v15, v16, v17
	v_fma_f32 v19, -v19, v22, v21
	v_add_f32_e32 v21, v14, v15
	v_mul_f32_e32 v14, 0x3d372713, v21
	v_mul_f32_e32 v14, v21, v14
	v_fma_f32 v14, v21, v14, v21
	v_mul_f32_e32 v14, 0x3f4c422a, v14
	v_add_f32_e32 v14, v14, v14
	v_mul_f32_e32 v14, 0x3fb8aa3b, v14
	v_exp_f32_e32 v14, v14
	v_div_fmas_f32 v15, v19, v20, v22
	v_div_fixup_f32 v15, v15, v18, 2.0
	v_sub_f32_e32 v15, 1.0, v15
	v_add_f32_e32 v18, 1.0, v14
	v_div_scale_f32 v19, s[42:43], v18, v18, 2.0
	v_rcp_f32_e32 v20, v19
	v_mul_f32_e32 v13, 0.5, v13
	v_add_f32_e32 v14, 1.0, v15
	v_mul_f32_e32 v13, v13, v14
	v_fma_f32 v14, -v19, v20, 1.0
	v_fmac_f32_e32 v20, v14, v20
	v_add_u32_e32 v14, 0x600, v86
	v_ashrrev_i32_e32 v24, 7, v14
	v_lshl_or_b32 v16, v24, 9, v4
	ds_read2st64_b32 v[14:15], v16 offset1:64
	ds_read2st64_b32 v[16:17], v16 offset0:128 offset1:192
	v_div_scale_f32 v22, vcc, 2.0, v18, 2.0
	v_mul_f32_e32 v23, v22, v20
	v_fma_f32 v25, -v19, v23, v22
	v_fmac_f32_e32 v23, v25, v20
	s_waitcnt lgkmcnt(1)
	v_add_f32_e32 v14, v14, v15
	s_waitcnt lgkmcnt(0)
	v_add_f32_e32 v15, v16, v17
	v_fma_f32 v19, -v19, v23, v22
	v_add_f32_e32 v22, v14, v15
	v_mul_f32_e32 v14, 0x3d372713, v22
	v_mul_f32_e32 v14, v22, v14
	v_fma_f32 v14, v22, v14, v22
	v_mul_f32_e32 v14, 0x3f4c422a, v14
	v_add_f32_e32 v14, v14, v14
	v_mul_f32_e32 v14, 0x3fb8aa3b, v14
	v_exp_f32_e32 v14, v14
	v_div_fmas_f32 v15, v19, v20, v23
	v_div_fixup_f32 v15, v15, v18, 2.0
	v_sub_f32_e32 v15, 1.0, v15
	v_add_f32_e32 v18, 1.0, v14
	v_div_scale_f32 v19, s[42:43], v18, v18, 2.0
	v_rcp_f32_e32 v20, v19
	v_mul_f32_e32 v14, 0.5, v21
	v_add_f32_e32 v15, 1.0, v15
	v_mul_f32_e32 v21, v14, v15
	v_fma_f32 v14, -v19, v20, 1.0
	v_fmac_f32_e32 v20, v14, v20
	v_add_u32_e32 v14, 0x700, v86
	v_ashrrev_i32_e32 v26, 7, v14
	v_lshl_or_b32 v16, v26, 9, v4
	ds_read2st64_b32 v[14:15], v16 offset1:64
	ds_read2st64_b32 v[16:17], v16 offset0:128 offset1:192
	v_div_scale_f32 v23, vcc, 2.0, v18, 2.0
	v_mul_f32_e32 v25, v23, v20
	v_fma_f32 v27, -v19, v25, v23
	v_fmac_f32_e32 v25, v27, v20
	s_waitcnt lgkmcnt(1)
	v_add_f32_e32 v14, v14, v15
	s_waitcnt lgkmcnt(0)
	v_add_f32_e32 v15, v16, v17
	v_fma_f32 v19, -v19, v25, v23
	v_add_f32_e32 v23, v14, v15
	v_mul_f32_e32 v14, 0x3d372713, v23
	v_mul_f32_e32 v14, v23, v14
	v_fma_f32 v14, v23, v14, v23
	v_mul_f32_e32 v14, 0x3f4c422a, v14
	v_add_f32_e32 v14, v14, v14
	v_mul_f32_e32 v14, 0x3fb8aa3b, v14
	v_exp_f32_e32 v14, v14
	v_div_fmas_f32 v15, v19, v20, v25
	v_div_fixup_f32 v15, v15, v18, 2.0
	v_sub_f32_e32 v15, 1.0, v15
	v_add_f32_e32 v18, 1.0, v14
	v_div_scale_f32 v19, s[42:43], v18, v18, 2.0
	v_rcp_f32_e32 v20, v19
	v_mul_f32_e32 v14, 0.5, v22
	v_add_f32_e32 v15, 1.0, v15
	v_mul_f32_e32 v22, v14, v15
	v_fma_f32 v14, -v19, v20, 1.0
	v_fmac_f32_e32 v20, v14, v20
	v_add_u32_e32 v14, 0x800, v86
	v_ashrrev_i32_e32 v28, 7, v14
	v_lshl_or_b32 v16, v28, 9, v4
	ds_read2st64_b32 v[14:15], v16 offset1:64
	ds_read2st64_b32 v[16:17], v16 offset0:128 offset1:192
	v_div_scale_f32 v25, vcc, 2.0, v18, 2.0
	v_mul_f32_e32 v27, v25, v20
	v_fma_f32 v29, -v19, v27, v25
	v_fmac_f32_e32 v27, v29, v20
	s_waitcnt lgkmcnt(1)
	v_add_f32_e32 v14, v14, v15
	s_waitcnt lgkmcnt(0)
	v_add_f32_e32 v15, v16, v17
	v_fma_f32 v19, -v19, v27, v25
	v_add_f32_e32 v25, v14, v15
	v_mul_f32_e32 v14, 0x3d372713, v25
	v_mul_f32_e32 v14, v25, v14
	v_fma_f32 v14, v25, v14, v25
	v_mul_f32_e32 v14, 0x3f4c422a, v14
	v_add_f32_e32 v14, v14, v14
	v_mul_f32_e32 v14, 0x3fb8aa3b, v14
	v_exp_f32_e32 v14, v14
	v_div_fmas_f32 v15, v19, v20, v27
	v_div_fixup_f32 v15, v15, v18, 2.0
	v_sub_f32_e32 v15, 1.0, v15
	v_add_f32_e32 v18, 1.0, v14
	v_div_scale_f32 v19, s[42:43], v18, v18, 2.0
	v_rcp_f32_e32 v20, v19
	v_mul_f32_e32 v14, 0.5, v23
	v_add_f32_e32 v15, 1.0, v15
	v_mul_f32_e32 v23, v14, v15
	v_fma_f32 v14, -v19, v20, 1.0
	v_fmac_f32_e32 v20, v14, v20
	v_add_u32_e32 v14, 0x900, v86
	v_ashrrev_i32_e32 v30, 7, v14
	v_lshl_or_b32 v16, v30, 9, v4
	ds_read2st64_b32 v[14:15], v16 offset1:64
	ds_read2st64_b32 v[16:17], v16 offset0:128 offset1:192
	v_div_scale_f32 v27, vcc, 2.0, v18, 2.0
	v_mul_f32_e32 v29, v27, v20
	v_fma_f32 v31, -v19, v29, v27
	v_fmac_f32_e32 v29, v31, v20
	s_waitcnt lgkmcnt(1)
	v_add_f32_e32 v14, v14, v15
	s_waitcnt lgkmcnt(0)
; DI float gelu_tanh(float x) {
;   const float u = 0.7978845608028654f * (x + 0.044715f * x * x * x);
;   const float e = __expf(2.f * u);
;   const float th = 1.f - 2.f / (e + 1.f);
;   return 0.5f * x * (1.f + th);
; }
; DI void cmp_tile(const Params& p, int l, int tile, char* smem) {
;     ...
;   float hv[16];
; #pragma unroll
;   for (int e = 0; e < 16; ++e) {
;     const int idx = tid + 256 * e, row = idx >> 7, col = idx & 127;
;     hv[e] = gelu_tanh((part[0][row][col] + part[1][row][col]) + (part[2][row][col] + part[3][row][col]));
;   }
	v_add_f32_e32 v15, v16, v17
	v_fma_f32 v19, -v19, v29, v27
	v_add_f32_e32 v27, v14, v15
	v_mul_f32_e32 v14, 0x3d372713, v27
	v_mul_f32_e32 v14, v27, v14
	v_fma_f32 v14, v27, v14, v27
	v_mul_f32_e32 v14, 0x3f4c422a, v14
	v_add_f32_e32 v14, v14, v14
	v_mul_f32_e32 v14, 0x3fb8aa3b, v14
	v_exp_f32_e32 v14, v14
	v_div_fmas_f32 v15, v19, v20, v29
	v_div_fixup_f32 v15, v15, v18, 2.0
	v_sub_f32_e32 v15, 1.0, v15
	v_add_f32_e32 v18, 1.0, v14
	v_div_scale_f32 v19, s[42:43], v18, v18, 2.0
	v_rcp_f32_e32 v20, v19
	v_mul_f32_e32 v14, 0.5, v25
	v_add_f32_e32 v15, 1.0, v15
	v_mul_f32_e32 v25, v14, v15
	v_fma_f32 v14, -v19, v20, 1.0
	v_fmac_f32_e32 v20, v14, v20
	v_add_u32_e32 v14, 0xa00, v86
	v_ashrrev_i32_e32 v32, 7, v14
	v_lshl_or_b32 v16, v32, 9, v4
	ds_read2st64_b32 v[14:15], v16 offset1:64
	ds_read2st64_b32 v[16:17], v16 offset0:128 offset1:192
	v_div_scale_f32 v29, vcc, 2.0, v18, 2.0
	v_mul_f32_e32 v31, v29, v20
	v_fma_f32 v33, -v19, v31, v29
	v_fmac_f32_e32 v31, v33, v20
	s_waitcnt lgkmcnt(1)
	v_add_f32_e32 v14, v14, v15
	s_waitcnt lgkmcnt(0)
	v_add_f32_e32 v15, v16, v17
	v_fma_f32 v19, -v19, v31, v29
	v_add_f32_e32 v29, v14, v15
	v_mul_f32_e32 v14, 0x3d372713, v29
	v_mul_f32_e32 v14, v29, v14
	v_fma_f32 v14, v29, v14, v29
	v_mul_f32_e32 v14, 0x3f4c422a, v14
	v_add_f32_e32 v14, v14, v14
	v_mul_f32_e32 v14, 0x3fb8aa3b, v14
	v_exp_f32_e32 v14, v14
	v_div_fmas_f32 v15, v19, v20, v31
	v_div_fixup_f32 v15, v15, v18, 2.0
	v_sub_f32_e32 v15, 1.0, v15
	v_add_f32_e32 v18, 1.0, v14
	v_div_scale_f32 v19, s[42:43], v18, v18, 2.0
	v_rcp_f32_e32 v20, v19
	v_mul_f32_e32 v14, 0.5, v27
	v_add_f32_e32 v15, 1.0, v15
	v_mul_f32_e32 v27, v14, v15
	v_fma_f32 v14, -v19, v20, 1.0
	v_fmac_f32_e32 v20, v14, v20
	v_add_u32_e32 v14, 0xb00, v86
	v_ashrrev_i32_e32 v34, 7, v14
	v_lshl_or_b32 v16, v34, 9, v4
	ds_read2st64_b32 v[14:15], v16 offset1:64
	ds_read2st64_b32 v[16:17], v16 offset0:128 offset1:192
	v_div_scale_f32 v31, vcc, 2.0, v18, 2.0
	v_mul_f32_e32 v33, v31, v20
	v_fma_f32 v35, -v19, v33, v31
	v_fmac_f32_e32 v33, v35, v20
	s_waitcnt lgkmcnt(1)
	v_add_f32_e32 v14, v14, v15
	s_waitcnt lgkmcnt(0)
	v_add_f32_e32 v15, v16, v17
	v_fma_f32 v19, -v19, v33, v31
	v_add_f32_e32 v31, v14, v15
	v_mul_f32_e32 v14, 0x3d372713, v31
	v_mul_f32_e32 v14, v31, v14
	v_fma_f32 v14, v31, v14, v31
	v_mul_f32_e32 v14, 0x3f4c422a, v14
	v_add_f32_e32 v14, v14, v14
	v_mul_f32_e32 v14, 0x3fb8aa3b, v14
	v_exp_f32_e32 v14, v14
	v_div_fmas_f32 v15, v19, v20, v33
	v_div_fixup_f32 v15, v15, v18, 2.0
	v_sub_f32_e32 v15, 1.0, v15
	v_add_f32_e32 v18, 1.0, v14
	v_div_scale_f32 v19, s[42:43], v18, v18, 2.0
	v_rcp_f32_e32 v20, v19
	v_mul_f32_e32 v14, 0.5, v29
	v_add_f32_e32 v15, 1.0, v15
	v_mul_f32_e32 v29, v14, v15
	v_fma_f32 v14, -v19, v20, 1.0
	v_fmac_f32_e32 v20, v14, v20
	v_add_u32_e32 v14, 0xc00, v86
	v_ashrrev_i32_e32 v36, 7, v14
	v_lshl_or_b32 v16, v36, 9, v4
	ds_read2st64_b32 v[14:15], v16 offset1:64
	ds_read2st64_b32 v[16:17], v16 offset0:128 offset1:192
	v_div_scale_f32 v33, vcc, 2.0, v18, 2.0
	v_mul_f32_e32 v35, v33, v20
	v_fma_f32 v37, -v19, v35, v33
	v_fmac_f32_e32 v35, v37, v20
	s_waitcnt lgkmcnt(1)
	v_add_f32_e32 v14, v14, v15
	s_waitcnt lgkmcnt(0)
	v_add_f32_e32 v15, v16, v17
	v_fma_f32 v19, -v19, v35, v33
	v_add_f32_e32 v33, v14, v15
	v_mul_f32_e32 v14, 0x3d372713, v33
	v_mul_f32_e32 v14, v33, v14
	v_fma_f32 v14, v33, v14, v33
	v_mul_f32_e32 v14, 0x3f4c422a, v14
	v_add_f32_e32 v14, v14, v14
	v_mul_f32_e32 v14, 0x3fb8aa3b, v14
	v_exp_f32_e32 v14, v14
	v_div_fmas_f32 v15, v19, v20, v35
	v_div_fixup_f32 v15, v15, v18, 2.0
	v_sub_f32_e32 v15, 1.0, v15
	v_add_f32_e32 v18, 1.0, v14
	v_div_scale_f32 v19, s[42:43], v18, v18, 2.0
	v_rcp_f32_e32 v20, v19
	v_mul_f32_e32 v14, 0.5, v31
	v_add_f32_e32 v15, 1.0, v15
	v_mul_f32_e32 v31, v14, v15
	v_fma_f32 v14, -v19, v20, 1.0
	v_fmac_f32_e32 v20, v14, v20
	v_add_u32_e32 v14, 0xd00, v86
	v_ashrrev_i32_e32 v38, 7, v14
	v_lshl_or_b32 v16, v38, 9, v4
	ds_read2st64_b32 v[14:15], v16 offset1:64
	ds_read2st64_b32 v[16:17], v16 offset0:128 offset1:192
	v_div_scale_f32 v35, vcc, 2.0, v18, 2.0
	v_mul_f32_e32 v37, v35, v20
	v_fma_f32 v39, -v19, v37, v35
	v_fmac_f32_e32 v37, v39, v20
	s_waitcnt lgkmcnt(1)
	v_add_f32_e32 v14, v14, v15
	s_waitcnt lgkmcnt(0)
	v_add_f32_e32 v15, v16, v17
	v_fma_f32 v19, -v19, v37, v35
	v_add_f32_e32 v35, v14, v15
	v_mul_f32_e32 v14, 0x3d372713, v35
	v_mul_f32_e32 v14, v35, v14
	v_fma_f32 v14, v35, v14, v35
	v_mul_f32_e32 v14, 0x3f4c422a, v14
	v_add_f32_e32 v14, v14, v14
	v_mul_f32_e32 v14, 0x3fb8aa3b, v14
	v_exp_f32_e32 v14, v14
	v_div_fmas_f32 v15, v19, v20, v37
	v_div_fixup_f32 v15, v15, v18, 2.0
	v_sub_f32_e32 v15, 1.0, v15
	v_add_f32_e32 v18, 1.0, v14
	v_div_scale_f32 v19, s[42:43], v18, v18, 2.0
	v_rcp_f32_e32 v20, v19
	v_mul_f32_e32 v14, 0.5, v33
	v_add_f32_e32 v15, 1.0, v15
	v_mul_f32_e32 v33, v14, v15
	v_fma_f32 v14, -v19, v20, 1.0
	v_fmac_f32_e32 v20, v14, v20
	v_add_u32_e32 v14, 0xe00, v86
	v_ashrrev_i32_e32 v40, 7, v14
	v_lshl_or_b32 v16, v40, 9, v4
	ds_read2st64_b32 v[14:15], v16 offset1:64
	ds_read2st64_b32 v[16:17], v16 offset0:128 offset1:192
	v_div_scale_f32 v37, vcc, 2.0, v18, 2.0
	v_mul_f32_e32 v39, v37, v20
	v_fma_f32 v41, -v19, v39, v37
	v_fmac_f32_e32 v39, v41, v20
	s_waitcnt lgkmcnt(1)
	v_add_f32_e32 v14, v14, v15
	s_waitcnt lgkmcnt(0)
; #define MFMA32(a, b, c) __builtin_amdgcn_mfma_f32_32x32x16_bf16((a), (b), (c), 0, 0, 0)
; DI unsigned pk2(float a, float b) { f32x2 v = {a, b}; bf2_t r = __builtin_convertvector(v, bf2_t); return __builtin_bit_cast(unsigned, r); }
; DI int crow(int i, int h) { return (i & 3) + 8 * (i >> 2) + 4 * h; }
; DI void cmp_tile(const Params& p, int l, int tile, char* smem) {
;     ...
;   __syncthreads();
; #pragma unroll
;   for (int e = 0; e < 16; ++e) {
;     const int idx = tid + 256 * e, row = idx >> 7, col = idx & 127;
;     hid[row][col] = (bf16_t)(pk2(hv[e], 0.f) & 0xffff);
;   }
;   __syncthreads();
;   if (w < 2) {
;     f32x16 a2;
; #pragma unroll
;     for (int i = 0; i < 16; ++i) a2[i] = 0.f;
; #pragma unroll
;     for (int ks = 0; ks < 8; ++ks) {
;       const bf16x8 av = *(const bf16x8*)&hid[r][ks * 16 + half * 8];
;       const bf16x8 bv = *(const bf16x8*)(W2T + (size_t)(32 * w + r) * 128 + ks * 16 + half * 8);
;       a2 = MFMA32(av, bv, a2);
;     }
; #pragma unroll
;     for (int i = 0; i < 16; ++i) outf[crow(i, half)][32 * w + r] = a2[i];
	v_add_f32_e32 v15, v16, v17
	v_fma_f32 v19, -v19, v39, v37
	v_add_f32_e32 v37, v14, v15
	v_mul_f32_e32 v14, 0x3d372713, v37
	v_mul_f32_e32 v14, v37, v14
	v_fma_f32 v14, v37, v14, v37
	v_mul_f32_e32 v14, 0x3f4c422a, v14
	v_add_f32_e32 v14, v14, v14
	v_mul_f32_e32 v14, 0x3fb8aa3b, v14
	v_exp_f32_e32 v14, v14
	v_div_fmas_f32 v15, v19, v20, v39
	v_div_fixup_f32 v15, v15, v18, 2.0
	v_sub_f32_e32 v15, 1.0, v15
	v_add_f32_e32 v18, 1.0, v14
	v_div_scale_f32 v19, s[42:43], v18, v18, 2.0
	v_rcp_f32_e32 v20, v19
	v_mul_f32_e32 v14, 0.5, v35
	v_add_f32_e32 v15, 1.0, v15
	v_mul_f32_e32 v35, v14, v15
	v_fma_f32 v14, -v19, v20, 1.0
	v_fmac_f32_e32 v20, v14, v20
	v_add_u32_e32 v14, 0xf00, v86
	v_ashrrev_i32_e32 v42, 7, v14
	v_lshl_or_b32 v4, v42, 9, v4
	ds_read2st64_b32 v[14:15], v4 offset1:64
	ds_read2st64_b32 v[16:17], v4 offset0:128 offset1:192
	v_div_scale_f32 v39, vcc, 2.0, v18, 2.0
	v_mul_f32_e32 v41, v39, v20
	s_waitcnt lgkmcnt(1)
	v_add_f32_e32 v14, v14, v15
	s_waitcnt lgkmcnt(0)
	v_add_f32_e32 v15, v16, v17
	v_add_f32_e32 v14, v14, v15
	v_mul_f32_e32 v15, 0x3d372713, v14
	v_mul_f32_e32 v15, v14, v15
	v_fma_f32 v15, v14, v15, v14
	v_mul_f32_e32 v15, 0x3f4c422a, v15
	v_add_f32_e32 v15, v15, v15
	v_mul_f32_e32 v15, 0x3fb8aa3b, v15
	v_exp_f32_e32 v15, v15
	v_fma_f32 v4, -v19, v41, v39
	v_fmac_f32_e32 v41, v4, v20
	v_fma_f32 v4, -v19, v41, v39
	v_add_f32_e32 v15, 1.0, v15
	v_div_scale_f32 v16, s[42:43], v15, v15, 2.0
	v_div_fmas_f32 v4, v4, v20, v41
	v_rcp_f32_e32 v17, v16
	v_div_fixup_f32 v4, v4, v18, 2.0
	v_sub_f32_e32 v4, 1.0, v4
	v_mul_f32_e32 v18, 0.5, v37
	v_add_f32_e32 v4, 1.0, v4
	v_mul_f32_e32 v18, v18, v4
	v_fma_f32 v4, -v16, v17, 1.0
	v_fmac_f32_e32 v17, v4, v17
	v_div_scale_f32 v4, vcc, 2.0, v15, 2.0
	v_mul_f32_e32 v19, v4, v17
	v_fma_f32 v20, -v16, v19, v4
	v_fmac_f32_e32 v19, v20, v17
	v_fma_f32 v4, -v16, v19, v4
	v_div_fmas_f32 v4, v4, v17, v19
	v_div_fixup_f32 v4, v4, v15, 2.0
	v_sub_f32_e32 v4, 1.0, v4
	v_mul_f32_e32 v14, 0.5, v14
	v_add_f32_e32 v4, 1.0, v4
	v_mul_f32_e32 v14, v14, v4
	v_cvt_pk_bf16_f32 v15, v5, s0
	v_mad_u64_u32 v[4:5], s[42:43], v0, s9, v[2:3]
	s_barrier
	ds_write_b16 v4, v15
	v_cvt_pk_bf16_f32 v0, v7, s0
	v_mad_u64_u32 v[4:5], s[42:43], v3, s9, v[2:3]
	ds_write_b16 v4, v0
	v_cvt_pk_bf16_f32 v0, v9, s0
	v_mad_u64_u32 v[4:5], s[42:43], v6, s9, v[2:3]
	ds_write_b16 v4, v0
	v_cvt_pk_bf16_f32 v0, v11, s0
	v_mad_u64_u32 v[4:5], s[42:43], v8, s9, v[2:3]
	ds_write_b16 v4, v0
	v_cvt_pk_bf16_f32 v0, v13, s0
	v_mad_u64_u32 v[4:5], s[42:43], v10, s9, v[2:3]
	ds_write_b16 v4, v0
	v_cvt_pk_bf16_f32 v0, v21, s0
	v_mad_u64_u32 v[4:5], s[42:43], v12, s9, v[2:3]
	ds_write_b16 v4, v0
	v_cvt_pk_bf16_f32 v0, v22, s0
	v_mad_u64_u32 v[4:5], s[42:43], v24, s9, v[2:3]
	ds_write_b16 v4, v0
	v_cvt_pk_bf16_f32 v0, v23, s0
	v_mad_u64_u32 v[4:5], s[42:43], v26, s9, v[2:3]
	ds_write_b16 v4, v0
	v_cvt_pk_bf16_f32 v0, v25, s0
	v_mad_u64_u32 v[4:5], s[42:43], v28, s9, v[2:3]
	ds_write_b16 v4, v0
	v_cvt_pk_bf16_f32 v0, v27, s0
	v_mad_u64_u32 v[4:5], s[42:43], v30, s9, v[2:3]
	ds_write_b16 v4, v0
	v_cvt_pk_bf16_f32 v0, v29, s0
	v_mad_u64_u32 v[4:5], s[42:43], v32, s9, v[2:3]
	ds_write_b16 v4, v0
	v_cvt_pk_bf16_f32 v0, v31, s0
	v_mad_u64_u32 v[4:5], s[42:43], v34, s9, v[2:3]
	ds_write_b16 v4, v0
	v_cvt_pk_bf16_f32 v0, v33, s0
	v_mad_u64_u32 v[4:5], s[42:43], v36, s9, v[2:3]
	ds_write_b16 v4, v0
	v_cvt_pk_bf16_f32 v0, v35, s0
	v_mad_u64_u32 v[4:5], s[42:43], v38, s9, v[2:3]
	ds_write_b16 v4, v0
	v_cvt_pk_bf16_f32 v0, v18, s0
	v_mad_u64_u32 v[4:5], s[42:43], v40, s9, v[2:3]
	ds_write_b16 v4, v0
	v_cvt_pk_bf16_f32 v0, v14, s0
	v_mad_u64_u32 v[2:3], s[42:43], v42, s9, v[2:3]
	v_cmp_gt_i32_e32 vcc, 2, v87
	ds_write_b16 v2, v0
	s_waitcnt lgkmcnt(0)
	s_barrier
	s_and_saveexec_b64 s[42:43], vcc
	s_cbranch_execz .LBB0_544
	s_and_b64 s[36:37], s[36:37], exec
	s_mov_b32 s9, 0x1f40000
	s_cselect_b32 s9, s9, 0x1f44000
	v_lshl_or_b32 v2, v87, 5, v88
	s_add_u32 s36, s26, s9
	v_ashrrev_i32_e32 v3, 31, v2
	s_addc_u32 s37, s27, 0
	v_lshlrev_b64 v[2:3], 8, v[2:3]
	v_lshlrev_b32_e32 v0, 4, v66
	v_lshl_add_u64 v[2:3], s[36:37], 0, v[2:3]
	v_lshl_add_u64 v[26:27], v[2:3], 0, v[0:1]
	global_load_dwordx4 v[2:5], v[26:27], off
	v_mad_u32_u24 v28, v88, s51, v0
	ds_read_b128 v[6:9], v28
	ds_read_b128 v[18:21], v28 offset:32
	global_load_dwordx4 v[22:25], v[26:27], off offset:32
	global_load_dwordx4 v[104:107], v[26:27], off offset:64
	global_load_dwordx4 v[108:111], v[26:27], off offset:96
	global_load_dwordx4 v[112:115], v[26:27], off offset:128
	global_load_dwordx4 v[116:119], v[26:27], off offset:160
	global_load_dwordx4 v[120:123], v[26:27], off offset:192
	global_load_dwordx4 v[124:127], v[26:27], off offset:224
	v_mul_u32_u24_e32 v0, 0x440, v66
	s_waitcnt vmcnt(7) lgkmcnt(1)
	v_mfma_f32_32x32x16_bf16 v[2:17], v[6:9], v[2:5], 0
	s_waitcnt vmcnt(6) lgkmcnt(0)
	v_mfma_f32_32x32x16_bf16 v[2:17], v[18:21], v[22:25], v[2:17]
	ds_read_b128 v[18:21], v28 offset:64
	s_waitcnt vmcnt(5) lgkmcnt(0)
	v_mfma_f32_32x32x16_bf16 v[2:17], v[18:21], v[104:107], v[2:17]
	ds_read_b128 v[18:21], v28 offset:96
	s_waitcnt vmcnt(4) lgkmcnt(0)
	v_mfma_f32_32x32x16_bf16 v[2:17], v[18:21], v[108:111], v[2:17]
	ds_read_b128 v[18:21], v28 offset:128
	s_waitcnt vmcnt(3) lgkmcnt(0)
	v_mfma_f32_32x32x16_bf16 v[2:17], v[18:21], v[112:115], v[2:17]
	ds_read_b128 v[18:21], v28 offset:160
	s_waitcnt vmcnt(2) lgkmcnt(0)
	v_mfma_f32_32x32x16_bf16 v[2:17], v[18:21], v[116:119], v[2:17]
	ds_read_b128 v[18:21], v28 offset:192
	s_waitcnt vmcnt(1) lgkmcnt(0)
	v_mfma_f32_32x32x16_bf16 v[2:17], v[18:21], v[120:123], v[2:17]
	ds_read_b128 v[18:21], v28 offset:224
	s_waitcnt vmcnt(0) lgkmcnt(0)
	v_mfma_f32_32x32x16_bf16 v[2:17], v[18:21], v[124:127], v[2:17]
	v_lshlrev_b32_e32 v18, 7, v87
	v_add3_u32 v0, v0, v18, v67
	v_add_u32_e32 v18, 0x2000, v0
	s_nop 8
	ds_write2_b32 v18, v2, v3 offset0:128 offset1:196
	v_add_u32_e32 v2, 0x2400, v0
	ds_write2_b32 v2, v4, v5 offset0:8 offset1:76
	v_add_u32_e32 v2, 0x2800, v0
	ds_write2_b32 v2, v6, v7 offset0:160 offset1:228
	v_add_u32_e32 v2, 0x2c00, v0
	ds_write2_b32 v2, v8, v9 offset0:40 offset1:108
	v_add_u32_e32 v2, 0x3200, v0
	ds_write2_b32 v2, v10, v11 offset0:64 offset1:132
	v_add_u32_e32 v2, 0x3400, v0
	ds_write2_b32 v2, v12, v13 offset0:72 offset1:140
	v_add_u32_e32 v2, 0x3a00, v0
	v_add_u32_e32 v0, 0x3c00, v0
	ds_write2_b32 v2, v14, v15 offset0:96 offset1:164
	ds_write2_b32 v0, v16, v17 offset0:104 offset1:172
